# fourier_pre rows warmed into L2 by two dummy loads per wave at the top of the spatial-gating chunk
# baseline (speedup 1.0000x reference)
.LBB0_310:
	v_lshlrev_b32_e32 v230, 7, v197
	v_lshl_add_u32 v230, v116, 14, v230
	v_add_u32_e32 v230, 0x4a60000, v230
	v_add_u32_e32 v233, 0x2000, v230
	global_load_dword v231, v230, s[30:31]
	global_load_dword v232, v233, s[30:31]
	v_add_u32_e32 v0, s3, v117
	v_mad_i64_i32 v[8:9], s[24:25], v0, s9, v[82:83]
	s_barrier
	global_load_dwordx4 v[0:3], v[8:9], off offset:1264
	global_load_dwordx4 v[4:7], v[8:9], off offset:1248
	global_load_dwordx4 v[10:13], v[8:9], off offset:1232
	global_load_dwordx4 v[14:17], v[8:9], off offset:1216
	global_load_dwordx4 v[214:217], v[8:9], off offset:1328
	global_load_dwordx4 v[218:221], v[8:9], off offset:1312
	global_load_dwordx4 v[222:225], v[8:9], off offset:1296
	global_load_dwordx4 v[226:229], v[8:9], off offset:1280
	global_load_dwordx4 v[94:97], v[66:67], off offset:48
	global_load_dwordx4 v[98:101], v[66:67], off offset:32
	global_load_dwordx4 v[102:105], v[66:67], off offset:16
	global_load_dwordx4 v[106:109], v[66:67], off
	global_load_dwordx4 v[110:113], v[66:67], off offset:112
	global_load_dwordx4 v[120:123], v[66:67], off offset:96
	global_load_dwordx4 v[124:127], v[66:67], off offset:80
	global_load_dwordx4 v[128:131], v[66:67], off offset:64
	global_load_dwordx4 v[132:135], v[66:67], off offset:176
	global_load_dwordx4 v[136:139], v[66:67], off offset:160
	global_load_dwordx4 v[140:143], v[66:67], off offset:144
	global_load_dwordx4 v[144:147], v[66:67], off offset:128
	global_load_dwordx4 v[148:151], v[66:67], off offset:224
	global_load_dwordx4 v[152:155], v[66:67], off offset:208
	global_load_dwordx4 v[162:165], v[66:67], off offset:192
	s_add_i32 s7, s7, s18
	s_waitcnt vmcnt(19)
	v_lshlrev_b32_e32 v18, 16, v14
	v_mul_f32_e32 v19, 0x3d372713, v18
	v_mul_f32_e32 v19, v19, v18
	v_fma_f32 v19, v19, v18, v18
	v_mul_f32_e32 v19, 0x3f4c422a, v19
	v_mul_f32_e32 v19, -2.0, v19
	v_mul_f32_e32 v19, 0x3fb8aa3b, v19
	v_exp_f32_e32 v19, v19
	v_and_b32_e32 v14, 0xffff0000, v14
	v_add_f32_e32 v19, 1.0, v19
	v_rcp_f32_e32 v19, v19
	s_nop 0
	v_mul_f32_e32 v24, v19, v18
	v_mul_f32_e32 v18, 0x3d372713, v14
	v_mul_f32_e32 v18, v18, v14
	v_fma_f32 v18, v18, v14, v14
	v_mul_f32_e32 v18, 0x3f4c422a, v18
	v_mul_f32_e32 v18, -2.0, v18
	v_mul_f32_e32 v18, 0x3fb8aa3b, v18
	v_exp_f32_e32 v18, v18
	s_nop 0
	v_add_f32_e32 v18, 1.0, v18
	v_rcp_f32_e32 v18, v18
	s_nop 0
	v_mul_f32_e32 v25, v18, v14
	v_lshlrev_b32_e32 v18, 16, v15
	v_mul_f32_e32 v19, 0x3d372713, v18
	v_mul_f32_e32 v19, v19, v18
	v_fma_f32 v19, v19, v18, v18
	v_mul_f32_e32 v19, 0x3f4c422a, v19
	v_mul_f32_e32 v19, -2.0, v19
	v_mul_f32_e32 v19, 0x3fb8aa3b, v19
	v_exp_f32_e32 v19, v19
	v_and_b32_e32 v15, 0xffff0000, v15
	v_mul_f32_e32 v14, v25, v25
	v_fmac_f32_e32 v14, v24, v24
	v_add_f32_e32 v19, 1.0, v19
	v_rcp_f32_e32 v19, v19
	s_nop 0
	v_mul_f32_e32 v26, v19, v18
	v_mul_f32_e32 v18, 0x3d372713, v15
	v_mul_f32_e32 v18, v18, v15
	v_fma_f32 v18, v18, v15, v15
	v_mul_f32_e32 v18, 0x3f4c422a, v18
	v_mul_f32_e32 v18, -2.0, v18
	v_mul_f32_e32 v18, 0x3fb8aa3b, v18
	v_exp_f32_e32 v18, v18
	s_nop 0
	v_add_f32_e32 v18, 1.0, v18
	v_rcp_f32_e32 v18, v18
	s_nop 0
	v_mul_f32_e32 v27, v18, v15
	v_mul_f32_e32 v15, v27, v27
	v_fmac_f32_e32 v15, v26, v26
	v_add_f32_e32 v14, v14, v15
	v_lshlrev_b32_e32 v15, 16, v16
	v_mul_f32_e32 v18, 0x3d372713, v15
	v_mul_f32_e32 v18, v18, v15
	v_fma_f32 v18, v18, v15, v15
	v_mul_f32_e32 v18, 0x3f4c422a, v18
	v_mul_f32_e32 v18, -2.0, v18
	v_mul_f32_e32 v18, 0x3fb8aa3b, v18
	v_exp_f32_e32 v18, v18
	s_nop 0
	v_add_f32_e32 v18, 1.0, v18
	v_rcp_f32_e32 v18, v18
	s_nop 0
	v_mul_f32_e32 v28, v18, v15
	v_and_b32_e32 v15, 0xffff0000, v16
	v_mul_f32_e32 v16, 0x3d372713, v15
	v_mul_f32_e32 v16, v16, v15
	v_fma_f32 v16, v16, v15, v15
	v_mul_f32_e32 v16, 0x3f4c422a, v16
	v_mul_f32_e32 v16, -2.0, v16
	v_mul_f32_e32 v16, 0x3fb8aa3b, v16
	v_exp_f32_e32 v16, v16
	s_nop 0
	v_add_f32_e32 v16, 1.0, v16
	v_rcp_f32_e32 v16, v16
	s_nop 0
	v_mul_f32_e32 v29, v16, v15
	v_mul_f32_e32 v15, v29, v29
	v_fmac_f32_e32 v15, v28, v28
	v_add_f32_e32 v14, v15, v14
	v_lshlrev_b32_e32 v15, 16, v17
	v_mul_f32_e32 v16, 0x3d372713, v15
	v_mul_f32_e32 v16, v16, v15
	v_fma_f32 v16, v16, v15, v15
	v_mul_f32_e32 v16, 0x3f4c422a, v16
	v_mul_f32_e32 v16, -2.0, v16
	v_mul_f32_e32 v16, 0x3fb8aa3b, v16
	v_exp_f32_e32 v16, v16
	s_nop 0
	v_add_f32_e32 v16, 1.0, v16
	v_rcp_f32_e32 v16, v16
	s_nop 0
	v_mul_f32_e32 v30, v16, v15
	v_and_b32_e32 v15, 0xffff0000, v17
	v_mul_f32_e32 v16, 0x3d372713, v15
	v_mul_f32_e32 v16, v16, v15
	v_fma_f32 v16, v16, v15, v15
	v_mul_f32_e32 v16, 0x3f4c422a, v16
	v_mul_f32_e32 v16, -2.0, v16
	v_mul_f32_e32 v16, 0x3fb8aa3b, v16
	v_exp_f32_e32 v16, v16
	s_nop 0
	v_add_f32_e32 v16, 1.0, v16
	v_rcp_f32_e32 v16, v16
	s_nop 0
	v_mul_f32_e32 v31, v16, v15
	v_mul_f32_e32 v15, v31, v31
	v_fmac_f32_e32 v15, v30, v30
	v_add_f32_e32 v14, v15, v14
	v_lshlrev_b32_e32 v15, 16, v10
	v_mul_f32_e32 v16, 0x3d372713, v15
	v_mul_f32_e32 v16, v16, v15
	v_fma_f32 v16, v16, v15, v15
	v_mul_f32_e32 v16, 0x3f4c422a, v16
	v_mul_f32_e32 v16, -2.0, v16
	v_mul_f32_e32 v16, 0x3fb8aa3b, v16
	v_exp_f32_e32 v16, v16
	v_and_b32_e32 v10, 0xffff0000, v10
	v_add_f32_e32 v16, 1.0, v16
	v_rcp_f32_e32 v16, v16
	s_nop 0
	v_mul_f32_e32 v32, v16, v15
	v_mul_f32_e32 v15, 0x3d372713, v10
	v_mul_f32_e32 v15, v15, v10
	v_fma_f32 v15, v15, v10, v10
	v_mul_f32_e32 v15, 0x3f4c422a, v15
	v_mul_f32_e32 v15, -2.0, v15
	v_mul_f32_e32 v15, 0x3fb8aa3b, v15
	v_exp_f32_e32 v15, v15
	s_nop 0
	v_add_f32_e32 v15, 1.0, v15
	v_rcp_f32_e32 v15, v15
	s_nop 0
	v_mul_f32_e32 v33, v15, v10
	v_mul_f32_e32 v10, v33, v33
	v_fmac_f32_e32 v10, v32, v32
	v_add_f32_e32 v10, v10, v14
	v_lshlrev_b32_e32 v14, 16, v11
	v_mul_f32_e32 v15, 0x3d372713, v14
	v_mul_f32_e32 v15, v15, v14
	v_fma_f32 v15, v15, v14, v14
	v_mul_f32_e32 v15, 0x3f4c422a, v15
	v_mul_f32_e32 v15, -2.0, v15
	v_mul_f32_e32 v15, 0x3fb8aa3b, v15
	v_exp_f32_e32 v15, v15
	v_and_b32_e32 v11, 0xffff0000, v11
	v_add_f32_e32 v15, 1.0, v15
	v_rcp_f32_e32 v15, v15
	s_nop 0
	v_mul_f32_e32 v34, v15, v14
	v_mul_f32_e32 v14, 0x3d372713, v11
	v_mul_f32_e32 v14, v14, v11
	v_fma_f32 v14, v14, v11, v11
	v_mul_f32_e32 v14, 0x3f4c422a, v14
	v_mul_f32_e32 v14, -2.0, v14
	v_mul_f32_e32 v14, 0x3fb8aa3b, v14
	v_exp_f32_e32 v14, v14
	s_nop 0
	v_add_f32_e32 v14, 1.0, v14
	v_rcp_f32_e32 v14, v14
	s_nop 0
	v_mul_f32_e32 v35, v14, v11
	v_mul_f32_e32 v11, v35, v35
	v_fmac_f32_e32 v11, v34, v34
	v_add_f32_e32 v10, v11, v10
	v_lshlrev_b32_e32 v11, 16, v12
	v_mul_f32_e32 v14, 0x3d372713, v11
	v_mul_f32_e32 v14, v14, v11
	v_fma_f32 v14, v14, v11, v11
	v_mul_f32_e32 v14, 0x3f4c422a, v14
	v_mul_f32_e32 v14, -2.0, v14
	v_mul_f32_e32 v14, 0x3fb8aa3b, v14
	v_exp_f32_e32 v14, v14
	s_nop 0
	v_add_f32_e32 v14, 1.0, v14
	v_rcp_f32_e32 v14, v14
	s_nop 0
	v_mul_f32_e32 v36, v14, v11
	v_and_b32_e32 v11, 0xffff0000, v12
	v_mul_f32_e32 v12, 0x3d372713, v11
	v_mul_f32_e32 v12, v12, v11
	v_fma_f32 v12, v12, v11, v11
	v_mul_f32_e32 v12, 0x3f4c422a, v12
	v_mul_f32_e32 v12, -2.0, v12
	v_mul_f32_e32 v12, 0x3fb8aa3b, v12
	v_exp_f32_e32 v12, v12
	s_nop 0
	v_add_f32_e32 v12, 1.0, v12
	v_rcp_f32_e32 v12, v12
	s_nop 0
	v_mul_f32_e32 v37, v12, v11
	v_mul_f32_e32 v11, v37, v37
	v_fmac_f32_e32 v11, v36, v36
	v_add_f32_e32 v10, v11, v10
	v_lshlrev_b32_e32 v11, 16, v13
	v_mul_f32_e32 v12, 0x3d372713, v11
	v_mul_f32_e32 v12, v12, v11
	v_fma_f32 v12, v12, v11, v11
	v_mul_f32_e32 v12, 0x3f4c422a, v12
	v_mul_f32_e32 v12, -2.0, v12
	v_mul_f32_e32 v12, 0x3fb8aa3b, v12
	v_exp_f32_e32 v12, v12
	s_nop 0
	v_add_f32_e32 v12, 1.0, v12
	v_rcp_f32_e32 v12, v12
	s_nop 0
	v_mul_f32_e32 v38, v12, v11
	v_and_b32_e32 v11, 0xffff0000, v13
	v_mul_f32_e32 v12, 0x3d372713, v11
	v_mul_f32_e32 v12, v12, v11
	v_fma_f32 v12, v12, v11, v11
	v_mul_f32_e32 v12, 0x3f4c422a, v12
	v_mul_f32_e32 v12, -2.0, v12
	v_mul_f32_e32 v12, 0x3fb8aa3b, v12
	v_exp_f32_e32 v12, v12
	s_nop 0
	v_add_f32_e32 v12, 1.0, v12
	v_rcp_f32_e32 v12, v12
	s_nop 0
	v_mul_f32_e32 v39, v12, v11
	v_mul_f32_e32 v11, v39, v39
	v_fmac_f32_e32 v11, v38, v38
	v_add_f32_e32 v10, v11, v10
	v_lshlrev_b32_e32 v11, 16, v4
	v_mul_f32_e32 v12, 0x3d372713, v11
	v_mul_f32_e32 v12, v12, v11
	v_fma_f32 v12, v12, v11, v11
	v_mul_f32_e32 v12, 0x3f4c422a, v12
	v_mul_f32_e32 v12, -2.0, v12
	v_mul_f32_e32 v12, 0x3fb8aa3b, v12
	v_exp_f32_e32 v12, v12
	v_and_b32_e32 v4, 0xffff0000, v4
	v_add_f32_e32 v12, 1.0, v12
	v_rcp_f32_e32 v12, v12
	s_nop 0
	v_mul_f32_e32 v40, v12, v11
	v_mul_f32_e32 v11, 0x3d372713, v4
	v_mul_f32_e32 v11, v11, v4
	v_fma_f32 v11, v11, v4, v4
	v_mul_f32_e32 v11, 0x3f4c422a, v11
	v_mul_f32_e32 v11, -2.0, v11
	v_mul_f32_e32 v11, 0x3fb8aa3b, v11
	v_exp_f32_e32 v11, v11
	s_nop 0
	v_add_f32_e32 v11, 1.0, v11
	v_rcp_f32_e32 v11, v11
	s_nop 0
	v_mul_f32_e32 v41, v11, v4
	v_mul_f32_e32 v4, v41, v41
	v_fmac_f32_e32 v4, v40, v40
	v_add_f32_e32 v4, v4, v10
	v_lshlrev_b32_e32 v10, 16, v5
	v_mul_f32_e32 v11, 0x3d372713, v10
	v_mul_f32_e32 v11, v11, v10
	v_fma_f32 v11, v11, v10, v10
	v_mul_f32_e32 v11, 0x3f4c422a, v11
	v_mul_f32_e32 v11, -2.0, v11
	v_mul_f32_e32 v11, 0x3fb8aa3b, v11
	v_exp_f32_e32 v11, v11
	v_and_b32_e32 v5, 0xffff0000, v5
	v_add_f32_e32 v11, 1.0, v11
	v_rcp_f32_e32 v11, v11
	s_nop 0
	v_mul_f32_e32 v42, v11, v10
	v_mul_f32_e32 v10, 0x3d372713, v5
	v_mul_f32_e32 v10, v10, v5
	v_fma_f32 v10, v10, v5, v5
	v_mul_f32_e32 v10, 0x3f4c422a, v10
	v_mul_f32_e32 v10, -2.0, v10
	v_mul_f32_e32 v10, 0x3fb8aa3b, v10
	v_exp_f32_e32 v10, v10
	s_nop 0
	v_add_f32_e32 v10, 1.0, v10
	v_rcp_f32_e32 v10, v10
	s_nop 0
	v_mul_f32_e32 v43, v10, v5
	v_mul_f32_e32 v5, v43, v43
	v_fmac_f32_e32 v5, v42, v42
	v_add_f32_e32 v4, v5, v4
	v_lshlrev_b32_e32 v5, 16, v6
	v_mul_f32_e32 v10, 0x3d372713, v5
	v_mul_f32_e32 v10, v10, v5
	v_fma_f32 v10, v10, v5, v5
	v_mul_f32_e32 v10, 0x3f4c422a, v10
	v_mul_f32_e32 v10, -2.0, v10
	v_mul_f32_e32 v10, 0x3fb8aa3b, v10
	v_exp_f32_e32 v10, v10
	s_nop 0
	v_add_f32_e32 v10, 1.0, v10
	v_rcp_f32_e32 v10, v10
	s_nop 0
	v_mul_f32_e32 v44, v10, v5
	v_and_b32_e32 v5, 0xffff0000, v6
	v_mul_f32_e32 v6, 0x3d372713, v5
	v_mul_f32_e32 v6, v6, v5
	v_fma_f32 v6, v6, v5, v5
	v_mul_f32_e32 v6, 0x3f4c422a, v6
	v_mul_f32_e32 v6, -2.0, v6
	v_mul_f32_e32 v6, 0x3fb8aa3b, v6
	v_exp_f32_e32 v6, v6
	s_nop 0
	v_add_f32_e32 v6, 1.0, v6
	v_rcp_f32_e32 v6, v6
	s_nop 0
	v_mul_f32_e32 v45, v6, v5
	v_mul_f32_e32 v5, v45, v45
	v_fmac_f32_e32 v5, v44, v44
	v_add_f32_e32 v4, v5, v4
	v_lshlrev_b32_e32 v5, 16, v7
	v_mul_f32_e32 v6, 0x3d372713, v5
	v_mul_f32_e32 v6, v6, v5
	v_fma_f32 v6, v6, v5, v5
	v_mul_f32_e32 v6, 0x3f4c422a, v6
	v_mul_f32_e32 v6, -2.0, v6
	v_mul_f32_e32 v6, 0x3fb8aa3b, v6
	v_exp_f32_e32 v6, v6
	s_nop 0
	v_add_f32_e32 v6, 1.0, v6
	v_rcp_f32_e32 v6, v6
	s_nop 0
	v_mul_f32_e32 v46, v6, v5
	v_and_b32_e32 v5, 0xffff0000, v7
	v_mul_f32_e32 v6, 0x3d372713, v5
	v_mul_f32_e32 v6, v6, v5
	v_fma_f32 v6, v6, v5, v5
	v_mul_f32_e32 v6, 0x3f4c422a, v6
	v_mul_f32_e32 v6, -2.0, v6
	v_mul_f32_e32 v6, 0x3fb8aa3b, v6
	v_exp_f32_e32 v6, v6
	s_nop 0
	v_add_f32_e32 v6, 1.0, v6
	v_rcp_f32_e32 v6, v6
	s_nop 0
	v_mul_f32_e32 v47, v6, v5
	v_mul_f32_e32 v5, v47, v47
	v_fmac_f32_e32 v5, v46, v46
	v_add_f32_e32 v4, v5, v4
	v_lshlrev_b32_e32 v5, 16, v0
	v_mul_f32_e32 v6, 0x3d372713, v5
	v_mul_f32_e32 v6, v6, v5
	v_fma_f32 v6, v6, v5, v5
	v_mul_f32_e32 v6, 0x3f4c422a, v6
	v_mul_f32_e32 v6, -2.0, v6
	v_mul_f32_e32 v6, 0x3fb8aa3b, v6
	v_exp_f32_e32 v6, v6
	v_and_b32_e32 v0, 0xffff0000, v0
	v_add_f32_e32 v6, 1.0, v6
	v_rcp_f32_e32 v6, v6
	s_nop 0
	v_mul_f32_e32 v48, v6, v5
	v_mul_f32_e32 v5, 0x3d372713, v0
	v_mul_f32_e32 v5, v5, v0
	v_fma_f32 v5, v5, v0, v0
	v_mul_f32_e32 v5, 0x3f4c422a, v5
	v_mul_f32_e32 v5, -2.0, v5
	v_mul_f32_e32 v5, 0x3fb8aa3b, v5
	v_exp_f32_e32 v5, v5
	s_nop 0
	v_add_f32_e32 v5, 1.0, v5
	v_rcp_f32_e32 v5, v5
	s_nop 0
	v_mul_f32_e32 v49, v5, v0
	v_mul_f32_e32 v0, v49, v49
	v_fmac_f32_e32 v0, v48, v48
	v_add_f32_e32 v0, v0, v4
	v_lshlrev_b32_e32 v4, 16, v1
	v_mul_f32_e32 v5, 0x3d372713, v4
	v_mul_f32_e32 v5, v5, v4
	v_fma_f32 v5, v5, v4, v4
	v_mul_f32_e32 v5, 0x3f4c422a, v5
	v_mul_f32_e32 v5, -2.0, v5
	v_mul_f32_e32 v5, 0x3fb8aa3b, v5
	v_exp_f32_e32 v5, v5
	v_and_b32_e32 v1, 0xffff0000, v1
	v_add_f32_e32 v5, 1.0, v5
	v_rcp_f32_e32 v5, v5
	s_nop 0
	v_mul_f32_e32 v50, v5, v4
	v_mul_f32_e32 v4, 0x3d372713, v1
	v_mul_f32_e32 v4, v4, v1
	v_fma_f32 v4, v4, v1, v1
	v_mul_f32_e32 v4, 0x3f4c422a, v4
	v_mul_f32_e32 v4, -2.0, v4
	v_mul_f32_e32 v4, 0x3fb8aa3b, v4
	v_exp_f32_e32 v4, v4
	s_nop 0
	v_add_f32_e32 v4, 1.0, v4
	v_rcp_f32_e32 v4, v4
	s_nop 0
	v_mul_f32_e32 v51, v4, v1
	v_mul_f32_e32 v1, v51, v51
	v_fmac_f32_e32 v1, v50, v50
	v_add_f32_e32 v0, v1, v0
	v_lshlrev_b32_e32 v1, 16, v2
	v_mul_f32_e32 v4, 0x3d372713, v1
	v_mul_f32_e32 v4, v4, v1
	v_fma_f32 v4, v4, v1, v1
	v_mul_f32_e32 v4, 0x3f4c422a, v4
	v_mul_f32_e32 v4, -2.0, v4
	v_mul_f32_e32 v4, 0x3fb8aa3b, v4
	v_exp_f32_e32 v4, v4
	s_nop 0
	v_add_f32_e32 v4, 1.0, v4
	v_rcp_f32_e32 v4, v4
	s_nop 0
	v_mul_f32_e32 v52, v4, v1
	v_and_b32_e32 v1, 0xffff0000, v2
	v_mul_f32_e32 v2, 0x3d372713, v1
	v_mul_f32_e32 v2, v2, v1
	v_fma_f32 v2, v2, v1, v1
	v_mul_f32_e32 v2, 0x3f4c422a, v2
	v_mul_f32_e32 v2, -2.0, v2
	v_mul_f32_e32 v2, 0x3fb8aa3b, v2
	v_exp_f32_e32 v2, v2
	s_nop 0
	v_add_f32_e32 v2, 1.0, v2
	v_rcp_f32_e32 v2, v2
	s_nop 0
	v_mul_f32_e32 v53, v2, v1
	v_mul_f32_e32 v1, v53, v53
	v_fmac_f32_e32 v1, v52, v52
	v_add_f32_e32 v0, v1, v0
	v_lshlrev_b32_e32 v1, 16, v3
	v_mul_f32_e32 v2, 0x3d372713, v1
	v_mul_f32_e32 v2, v2, v1
	v_fma_f32 v2, v2, v1, v1
	v_mul_f32_e32 v2, 0x3f4c422a, v2
	v_mul_f32_e32 v2, -2.0, v2
	v_mul_f32_e32 v2, 0x3fb8aa3b, v2
	v_exp_f32_e32 v2, v2
	s_nop 0
	v_add_f32_e32 v2, 1.0, v2
	v_rcp_f32_e32 v2, v2
	s_nop 0
	v_mul_f32_e32 v54, v2, v1
	v_and_b32_e32 v1, 0xffff0000, v3
	v_mul_f32_e32 v2, 0x3d372713, v1
	v_mul_f32_e32 v2, v2, v1
	v_fma_f32 v2, v2, v1, v1
	v_mul_f32_e32 v2, 0x3f4c422a, v2
	v_mul_f32_e32 v2, -2.0, v2
	v_mul_f32_e32 v2, 0x3fb8aa3b, v2
	v_exp_f32_e32 v2, v2
	s_nop 0
	v_add_f32_e32 v2, 1.0, v2
	v_rcp_f32_e32 v2, v2
	s_nop 0
	v_mul_f32_e32 v55, v2, v1
	v_mul_f32_e32 v1, v55, v55
	v_fmac_f32_e32 v1, v54, v54
	v_add_f32_e32 v18, v1, v0
	s_waitcnt vmcnt(15)
	v_mov_b32_e32 v0, v214
	v_mov_b32_e32 v1, v215
	v_mov_b32_e32 v2, v216
	v_mov_b32_e32 v3, v217
	v_mov_b32_e32 v4, v218
	v_mov_b32_e32 v5, v219
	v_mov_b32_e32 v6, v220
	v_mov_b32_e32 v7, v221
	v_mov_b32_e32 v10, v222
	v_mov_b32_e32 v11, v223
	v_mov_b32_e32 v12, v224
	v_mov_b32_e32 v13, v225
	v_mov_b32_e32 v14, v226
	v_mov_b32_e32 v15, v227
	v_mov_b32_e32 v16, v228
	v_mov_b32_e32 v17, v229
	v_lshlrev_b32_e32 v8, 16, v14
	v_mul_f32_e32 v9, 0x3d372713, v8
	v_mul_f32_e32 v9, v9, v8
	v_fma_f32 v9, v9, v8, v8
	v_mul_f32_e32 v9, 0x3f4c422a, v9
	v_mul_f32_e32 v9, -2.0, v9
	v_mul_f32_e32 v9, 0x3fb8aa3b, v9
	v_exp_f32_e32 v9, v9
	s_nop 0
	v_add_f32_e32 v9, 1.0, v9
	v_rcp_f32_e32 v9, v9
	s_nop 0
	v_mul_f32_e32 v56, v9, v8
	v_and_b32_e32 v8, 0xffff0000, v14
	v_mul_f32_e32 v9, 0x3d372713, v8
	v_mul_f32_e32 v9, v9, v8
	v_fma_f32 v9, v9, v8, v8
	v_mul_f32_e32 v9, 0x3f4c422a, v9
	v_mul_f32_e32 v9, -2.0, v9
	v_mul_f32_e32 v9, 0x3fb8aa3b, v9
	v_exp_f32_e32 v9, v9
	s_nop 0
	v_add_f32_e32 v9, 1.0, v9
	v_rcp_f32_e32 v9, v9
	s_nop 0
	v_mul_f32_e32 v57, v9, v8
	v_lshlrev_b32_e32 v9, 16, v15
	v_mul_f32_e32 v14, 0x3d372713, v9
	v_mul_f32_e32 v14, v14, v9
	v_fma_f32 v14, v14, v9, v9
	v_mul_f32_e32 v14, 0x3f4c422a, v14
	v_mul_f32_e32 v14, -2.0, v14
	v_mul_f32_e32 v14, 0x3fb8aa3b, v14
	v_exp_f32_e32 v14, v14
	v_mul_f32_e32 v8, v57, v57
	v_fmac_f32_e32 v8, v56, v56
	v_add_f32_e32 v8, v8, v18
	v_add_f32_e32 v14, 1.0, v14
	v_rcp_f32_e32 v14, v14
	s_nop 0
	v_mul_f32_e32 v58, v14, v9
	v_and_b32_e32 v9, 0xffff0000, v15
	v_mul_f32_e32 v14, 0x3d372713, v9
	v_mul_f32_e32 v14, v14, v9
	v_fma_f32 v14, v14, v9, v9
	v_mul_f32_e32 v14, 0x3f4c422a, v14
	v_mul_f32_e32 v14, -2.0, v14
	v_mul_f32_e32 v14, 0x3fb8aa3b, v14
	v_exp_f32_e32 v14, v14
	s_nop 0
	v_add_f32_e32 v14, 1.0, v14
	v_rcp_f32_e32 v14, v14
	s_nop 0
	v_mul_f32_e32 v59, v14, v9
	v_mul_f32_e32 v9, v59, v59
	v_fmac_f32_e32 v9, v58, v58
	v_add_f32_e32 v8, v9, v8
	v_lshlrev_b32_e32 v9, 16, v16
	v_mul_f32_e32 v14, 0x3d372713, v9
	v_mul_f32_e32 v14, v14, v9
	v_fma_f32 v14, v14, v9, v9
	v_mul_f32_e32 v14, 0x3f4c422a, v14
	v_mul_f32_e32 v14, -2.0, v14
	v_mul_f32_e32 v14, 0x3fb8aa3b, v14
	v_exp_f32_e32 v14, v14
	s_nop 0
	v_add_f32_e32 v14, 1.0, v14
	v_rcp_f32_e32 v14, v14
	s_nop 0
	v_mul_f32_e32 v60, v14, v9
	v_and_b32_e32 v9, 0xffff0000, v16
	v_mul_f32_e32 v14, 0x3d372713, v9
	v_mul_f32_e32 v14, v14, v9
	v_fma_f32 v14, v14, v9, v9
	v_mul_f32_e32 v14, 0x3f4c422a, v14
	v_mul_f32_e32 v14, -2.0, v14
	v_mul_f32_e32 v14, 0x3fb8aa3b, v14
	v_exp_f32_e32 v14, v14
	s_nop 0
	v_add_f32_e32 v14, 1.0, v14
	v_rcp_f32_e32 v14, v14
	s_nop 0
	v_mul_f32_e32 v61, v14, v9
	v_mul_f32_e32 v9, v61, v61
	v_fmac_f32_e32 v9, v60, v60
	v_add_f32_e32 v8, v9, v8
	v_lshlrev_b32_e32 v9, 16, v17
	v_mul_f32_e32 v14, 0x3d372713, v9
	v_mul_f32_e32 v14, v14, v9
	v_fma_f32 v14, v14, v9, v9
	v_mul_f32_e32 v14, 0x3f4c422a, v14
	v_mul_f32_e32 v14, -2.0, v14
	v_mul_f32_e32 v14, 0x3fb8aa3b, v14
	v_exp_f32_e32 v14, v14
	s_nop 0
	v_add_f32_e32 v14, 1.0, v14
	v_rcp_f32_e32 v14, v14
	s_nop 0
	v_mul_f32_e32 v62, v14, v9
	v_and_b32_e32 v9, 0xffff0000, v17
	v_mul_f32_e32 v14, 0x3d372713, v9
	v_mul_f32_e32 v14, v14, v9
	v_fma_f32 v14, v14, v9, v9
	v_mul_f32_e32 v14, 0x3f4c422a, v14
	v_mul_f32_e32 v14, -2.0, v14
	v_mul_f32_e32 v14, 0x3fb8aa3b, v14
	v_exp_f32_e32 v14, v14
	v_and_b32_e32 v17, 0xffff0000, v5
	v_add_f32_e32 v14, 1.0, v14
	v_rcp_f32_e32 v14, v14
	s_nop 0
	v_mul_f32_e32 v63, v14, v9
	v_mul_f32_e32 v9, v63, v63
	v_fmac_f32_e32 v9, v62, v62
	v_add_f32_e32 v8, v9, v8
	v_lshlrev_b32_e32 v9, 16, v10
	v_mul_f32_e32 v14, 0x3d372713, v9
	v_mul_f32_e32 v14, v14, v9
	v_fma_f32 v14, v14, v9, v9
	v_mul_f32_e32 v14, 0x3f4c422a, v14
	v_mul_f32_e32 v14, -2.0, v14
	v_mul_f32_e32 v14, 0x3fb8aa3b, v14
	v_exp_f32_e32 v14, v14
	s_nop 0
	v_add_f32_e32 v14, 1.0, v14
	v_rcp_f32_e32 v14, v14
	s_nop 0
	v_mul_f32_e32 v88, v14, v9
	v_and_b32_e32 v9, 0xffff0000, v10
	v_mul_f32_e32 v10, 0x3d372713, v9
	v_mul_f32_e32 v10, v10, v9
	v_fma_f32 v10, v10, v9, v9
	v_mul_f32_e32 v10, 0x3f4c422a, v10
	v_mul_f32_e32 v10, -2.0, v10
	v_mul_f32_e32 v10, 0x3fb8aa3b, v10
	v_exp_f32_e32 v10, v10
	s_nop 0
	v_add_f32_e32 v10, 1.0, v10
	v_rcp_f32_e32 v10, v10
	s_nop 0
	v_mul_f32_e32 v89, v10, v9
	v_mul_f32_e32 v9, v89, v89
	v_fmac_f32_e32 v9, v88, v88
	v_add_f32_e32 v8, v9, v8
	v_lshlrev_b32_e32 v9, 16, v11
	v_mul_f32_e32 v10, 0x3d372713, v9
	v_mul_f32_e32 v10, v10, v9
	v_fma_f32 v10, v10, v9, v9
	v_mul_f32_e32 v10, 0x3f4c422a, v10
	v_mul_f32_e32 v10, -2.0, v10
	v_mul_f32_e32 v10, 0x3fb8aa3b, v10
	v_exp_f32_e32 v10, v10
	s_nop 0
	v_add_f32_e32 v10, 1.0, v10
	v_rcp_f32_e32 v10, v10
	s_nop 0
	v_mul_f32_e32 v90, v10, v9
	v_and_b32_e32 v9, 0xffff0000, v11
	v_mul_f32_e32 v10, 0x3d372713, v9
	v_mul_f32_e32 v10, v10, v9
	v_fma_f32 v10, v10, v9, v9
	v_mul_f32_e32 v10, 0x3f4c422a, v10
	v_mul_f32_e32 v10, -2.0, v10
	v_mul_f32_e32 v10, 0x3fb8aa3b, v10
	v_exp_f32_e32 v10, v10
	s_nop 0
	v_add_f32_e32 v10, 1.0, v10
	v_rcp_f32_e32 v10, v10
	s_nop 0
	v_mul_f32_e32 v91, v10, v9
	v_mul_f32_e32 v9, v91, v91
	v_fmac_f32_e32 v9, v90, v90
	v_add_f32_e32 v16, v9, v8
	v_lshlrev_b32_e32 v8, 16, v12
	v_mul_f32_e32 v10, 0x3d372713, v8
	v_mul_f32_e32 v10, v10, v8
	v_mov_b32_e32 v11, v8
	v_fmac_f32_e32 v11, v10, v11
	v_and_b32_e32 v12, 0xffff0000, v12
	v_mul_f32_e32 v10, 0x3f4c422a, v11
	v_mul_f32_e32 v11, 0x3d372713, v12
	v_mul_f32_e32 v11, v11, v12
	v_mov_b32_e32 v14, v12
	v_fmac_f32_e32 v14, v11, v14
	v_mul_f32_e32 v11, 0x3f4c422a, v14
	v_mul_f32_e32 v11, -2.0, v11
	v_mul_f32_e32 v11, 0x3fb8aa3b, v11
	v_exp_f32_e32 v11, v11
	v_lshlrev_b32_e32 v9, 16, v13
	v_mov_b32_e32 v15, v9
	v_mul_f32_e32 v10, -2.0, v10
	v_add_f32_e32 v11, 1.0, v11
	v_rcp_f32_e32 v14, v11
	v_mul_f32_e32 v11, 0x3d372713, v9
	v_mul_f32_e32 v11, v11, v9
	v_fmac_f32_e32 v15, v11, v15
	v_mul_f32_e32 v11, 0x3f4c422a, v15
	v_mul_f32_e32 v11, -2.0, v11
	v_mul_f32_e32 v10, 0x3fb8aa3b, v10
	v_mul_f32_e32 v11, 0x3fb8aa3b, v11
	v_exp_f32_e32 v10, v10
	v_exp_f32_e32 v11, v11
	v_and_b32_e32 v13, 0xffff0000, v13
	v_add_f32_e32 v10, 1.0, v10
	v_add_f32_e32 v11, 1.0, v11
	v_rcp_f32_e32 v10, v10
	v_rcp_f32_e32 v11, v11
	s_nop 0
	v_pk_mul_f32 v[8:9], v[10:11], v[8:9]
	v_mul_f32_e32 v10, 0x3d372713, v13
	v_mul_f32_e32 v10, v10, v13
	v_mov_b32_e32 v11, v13
	v_fmac_f32_e32 v11, v10, v11
	v_mul_f32_e32 v10, 0x3f4c422a, v11
	v_mul_f32_e32 v10, -2.0, v10
	v_mul_f32_e32 v10, 0x3fb8aa3b, v10
	v_exp_f32_e32 v10, v10
	s_nop 0
	v_add_f32_e32 v10, 1.0, v10
	v_rcp_f32_e32 v15, v10
	s_nop 0
	v_pk_mul_f32 v[10:11], v[14:15], v[12:13]
	s_nop 0
	v_pk_mul_f32 v[12:13], v[10:11], v[10:11]
	s_nop 0
	v_pk_fma_f32 v[12:13], v[8:9], v[8:9], v[12:13]
	s_nop 0
	v_add_f32_e32 v12, v12, v16
	v_and_b32_e32 v16, 0xffff0000, v4
	v_add_f32_e32 v20, v13, v12
	v_lshlrev_b32_e32 v12, 16, v4
	v_mul_f32_e32 v4, 0x3d372713, v16
	v_lshlrev_b32_e32 v13, 16, v5
	v_mul_f32_e32 v4, v4, v16
	v_mov_b32_e32 v5, v16
	v_fmac_f32_e32 v5, v4, v5
	v_mul_f32_e32 v4, 0x3f4c422a, v5
	v_mul_f32_e32 v4, -2.0, v4
	v_mul_f32_e32 v4, 0x3fb8aa3b, v4
	v_exp_f32_e32 v4, v4
	v_mul_f32_e32 v14, 0x3d372713, v12
	v_mul_f32_e32 v14, v14, v12
	v_mov_b32_e32 v15, v12
	v_add_f32_e32 v4, 1.0, v4
	v_rcp_f32_e32 v18, v4
	v_mul_f32_e32 v4, 0x3d372713, v13
	v_mul_f32_e32 v4, v4, v13
	v_mov_b32_e32 v5, v13
	v_fmac_f32_e32 v15, v14, v15
	v_fmac_f32_e32 v5, v4, v5
	v_mul_f32_e32 v14, 0x3f4c422a, v15
	v_mul_f32_e32 v4, 0x3f4c422a, v5
	v_mul_f32_e32 v14, -2.0, v14
	v_mul_f32_e32 v4, -2.0, v4
	v_mul_f32_e32 v14, 0x3fb8aa3b, v14
	v_mul_f32_e32 v4, 0x3fb8aa3b, v4
	v_exp_f32_e32 v14, v14
	v_exp_f32_e32 v4, v4
	v_add_f32_e32 v14, 1.0, v14
	v_add_f32_e32 v4, 1.0, v4
	v_rcp_f32_e32 v14, v14
	v_rcp_f32_e32 v15, v4
	s_nop 0
	v_pk_mul_f32 v[4:5], v[14:15], v[12:13]
	v_mul_f32_e32 v12, 0x3d372713, v17
	v_mul_f32_e32 v12, v12, v17
	v_mov_b32_e32 v13, v17
	v_fmac_f32_e32 v13, v12, v13
	v_mul_f32_e32 v12, 0x3f4c422a, v13
	v_mul_f32_e32 v12, -2.0, v12
	v_mul_f32_e32 v12, 0x3fb8aa3b, v12
	v_exp_f32_e32 v12, v12
	s_nop 0
	v_add_f32_e32 v12, 1.0, v12
	v_rcp_f32_e32 v19, v12
	s_nop 0
	v_pk_mul_f32 v[12:13], v[18:19], v[16:17]
	s_nop 0
	v_pk_mul_f32 v[14:15], v[12:13], v[12:13]
	v_and_b32_e32 v18, 0xffff0000, v6
	v_pk_fma_f32 v[14:15], v[4:5], v[4:5], v[14:15]
	v_and_b32_e32 v19, 0xffff0000, v7
	v_add_f32_e32 v14, v14, v20
	v_add_f32_e32 v22, v15, v14
	v_lshlrev_b32_e32 v14, 16, v6
	v_mul_f32_e32 v6, 0x3d372713, v18
	v_lshlrev_b32_e32 v15, 16, v7
	v_mul_f32_e32 v6, v6, v18
	v_mov_b32_e32 v7, v18
	v_fmac_f32_e32 v7, v6, v7
	v_mul_f32_e32 v6, 0x3f4c422a, v7
	v_mul_f32_e32 v6, -2.0, v6
	v_mul_f32_e32 v6, 0x3fb8aa3b, v6
	v_exp_f32_e32 v6, v6
	v_mul_f32_e32 v16, 0x3d372713, v14
	v_mul_f32_e32 v16, v16, v14
	v_mov_b32_e32 v17, v14
	v_add_f32_e32 v6, 1.0, v6
	v_rcp_f32_e32 v20, v6
	v_mul_f32_e32 v6, 0x3d372713, v15
	v_mul_f32_e32 v6, v6, v15
	v_mov_b32_e32 v7, v15
	v_fmac_f32_e32 v17, v16, v17
	v_fmac_f32_e32 v7, v6, v7
	v_mul_f32_e32 v16, 0x3f4c422a, v17
	v_mul_f32_e32 v6, 0x3f4c422a, v7
	v_mul_f32_e32 v16, -2.0, v16
	v_mul_f32_e32 v6, -2.0, v6
	v_mul_f32_e32 v16, 0x3fb8aa3b, v16
	v_mul_f32_e32 v6, 0x3fb8aa3b, v6
	v_exp_f32_e32 v16, v16
	v_exp_f32_e32 v6, v6
	v_add_f32_e32 v16, 1.0, v16
	v_add_f32_e32 v6, 1.0, v6
	v_rcp_f32_e32 v16, v16
	v_rcp_f32_e32 v17, v6
	s_nop 0
	v_pk_mul_f32 v[6:7], v[16:17], v[14:15]
	v_mul_f32_e32 v14, 0x3d372713, v19
	v_mul_f32_e32 v14, v14, v19
	v_mov_b32_e32 v15, v19
	v_fmac_f32_e32 v15, v14, v15
	v_mul_f32_e32 v14, 0x3f4c422a, v15
	v_mul_f32_e32 v14, -2.0, v14
	v_mul_f32_e32 v14, 0x3fb8aa3b, v14
	v_exp_f32_e32 v14, v14
	s_nop 0
	v_add_f32_e32 v14, 1.0, v14
	v_rcp_f32_e32 v21, v14
	s_nop 0
	v_pk_mul_f32 v[14:15], v[20:21], v[18:19]
	s_nop 0
	v_pk_mul_f32 v[16:17], v[14:15], v[14:15]
	s_nop 0
	v_pk_fma_f32 v[16:17], v[6:7], v[6:7], v[16:17]
	s_nop 0
	v_add_f32_e32 v16, v16, v22
	v_add_f32_e32 v22, v17, v16
	v_lshlrev_b32_e32 v16, 16, v0
	v_mul_f32_e32 v18, 0x3d372713, v16
	v_mul_f32_e32 v18, v18, v16
	v_mov_b32_e32 v19, v16
	v_fmac_f32_e32 v19, v18, v19
	v_and_b32_e32 v0, 0xffff0000, v0
	v_mul_f32_e32 v18, 0x3f4c422a, v19
	v_mul_f32_e32 v19, 0x3d372713, v0
	v_mul_f32_e32 v19, v19, v0
	v_mov_b32_e32 v20, v0
	v_fmac_f32_e32 v20, v19, v20
	v_mul_f32_e32 v19, 0x3f4c422a, v20
	v_mul_f32_e32 v19, -2.0, v19
	v_mul_f32_e32 v19, 0x3fb8aa3b, v19
	v_exp_f32_e32 v19, v19
	v_lshlrev_b32_e32 v17, 16, v1
	v_mov_b32_e32 v21, v17
	v_mul_f32_e32 v18, -2.0, v18
	v_add_f32_e32 v19, 1.0, v19
	v_rcp_f32_e32 v20, v19
	v_mul_f32_e32 v19, 0x3d372713, v17
	v_mul_f32_e32 v19, v19, v17
	v_fmac_f32_e32 v21, v19, v21
	v_mul_f32_e32 v19, 0x3f4c422a, v21
	v_mul_f32_e32 v19, -2.0, v19
	v_mul_f32_e32 v18, 0x3fb8aa3b, v18
	v_mul_f32_e32 v19, 0x3fb8aa3b, v19
	v_exp_f32_e32 v18, v18
	v_exp_f32_e32 v19, v19
	v_and_b32_e32 v1, 0xffff0000, v1
	v_add_f32_e32 v18, 1.0, v18
	v_add_f32_e32 v19, 1.0, v19
	v_rcp_f32_e32 v18, v18
	v_rcp_f32_e32 v19, v19
	s_nop 0
	v_pk_mul_f32 v[16:17], v[18:19], v[16:17]
	v_mul_f32_e32 v18, 0x3d372713, v1
	v_mul_f32_e32 v18, v18, v1
	v_mov_b32_e32 v19, v1
	v_fmac_f32_e32 v19, v18, v19
	v_mul_f32_e32 v18, 0x3f4c422a, v19
	v_mul_f32_e32 v18, -2.0, v18
	v_mul_f32_e32 v18, 0x3fb8aa3b, v18
	v_exp_f32_e32 v18, v18
	s_nop 0
	v_add_f32_e32 v18, 1.0, v18
	v_rcp_f32_e32 v21, v18
	s_nop 0
	v_pk_mul_f32 v[18:19], v[20:21], v[0:1]
	s_nop 0
	v_pk_mul_f32 v[0:1], v[18:19], v[18:19]
	s_nop 0
	v_pk_fma_f32 v[0:1], v[16:17], v[16:17], v[0:1]
	s_nop 0
	v_add_f32_e32 v0, v0, v22
	v_add_f32_e32 v92, v1, v0
	v_lshlrev_b32_e32 v0, 16, v2
	v_mul_f32_e32 v20, 0x3d372713, v0
	v_mul_f32_e32 v20, v20, v0
	v_mov_b32_e32 v21, v0
	v_fmac_f32_e32 v21, v20, v21
	v_and_b32_e32 v2, 0xffff0000, v2
	v_mul_f32_e32 v20, 0x3f4c422a, v21
	v_mul_f32_e32 v21, 0x3d372713, v2
	v_mul_f32_e32 v21, v21, v2
	v_mov_b32_e32 v22, v2
	v_fmac_f32_e32 v22, v21, v22
	v_mul_f32_e32 v21, 0x3f4c422a, v22
	v_mul_f32_e32 v21, -2.0, v21
	v_mul_f32_e32 v21, 0x3fb8aa3b, v21
	v_exp_f32_e32 v21, v21
	v_lshlrev_b32_e32 v1, 16, v3
	v_mov_b32_e32 v23, v1
	v_mul_f32_e32 v20, -2.0, v20
	v_add_f32_e32 v21, 1.0, v21
	v_rcp_f32_e32 v22, v21
	v_mul_f32_e32 v21, 0x3d372713, v1
	v_mul_f32_e32 v21, v21, v1
	v_fmac_f32_e32 v23, v21, v23
	v_mul_f32_e32 v21, 0x3f4c422a, v23
	v_mul_f32_e32 v21, -2.0, v21
	v_mul_f32_e32 v20, 0x3fb8aa3b, v20
	v_mul_f32_e32 v21, 0x3fb8aa3b, v21
	v_exp_f32_e32 v20, v20
	v_exp_f32_e32 v21, v21
	v_and_b32_e32 v3, 0xffff0000, v3
	v_add_f32_e32 v20, 1.0, v20
	v_add_f32_e32 v21, 1.0, v21
	v_rcp_f32_e32 v20, v20
	v_rcp_f32_e32 v21, v21
	s_nop 0
	v_pk_mul_f32 v[20:21], v[20:21], v[0:1]
	v_mul_f32_e32 v0, 0x3d372713, v3
	v_mul_f32_e32 v0, v0, v3
	v_mov_b32_e32 v1, v3
	v_fmac_f32_e32 v1, v0, v1
	v_mul_f32_e32 v0, 0x3f4c422a, v1
	v_mul_f32_e32 v0, -2.0, v0
	v_mul_f32_e32 v0, 0x3fb8aa3b, v0
	v_exp_f32_e32 v0, v0
	s_nop 0
	v_add_f32_e32 v0, 1.0, v0
	v_rcp_f32_e32 v23, v0
	s_nop 0
	v_pk_mul_f32 v[22:23], v[22:23], v[2:3]
	s_nop 0
	v_pk_mul_f32 v[0:1], v[22:23], v[22:23]
	s_nop 0
	v_pk_fma_f32 v[0:1], v[20:21], v[20:21], v[0:1]
	s_nop 0
	v_add_f32_e32 v0, v0, v92
	v_add_f32_e32 v0, v1, v0
	v_fmamk_f32 v0, v0, 0x3c800000, v158
	v_cmp_gt_f32_e32 vcc, s82, v0
	v_mul_f32_e32 v1, 0x4b800000, v0
	s_nop 0
	v_cndmask_b32_e32 v0, v0, v1, vcc
	v_rsq_f32_e32 v92, v0
	global_load_dwordx4 v[0:3], v[66:67], off offset:240
	v_mul_f32_e32 v93, 0x45800000, v92
	v_cndmask_b32_e32 v92, v92, v93, vcc
	v_mul_f32_e32 v24, v24, v92
	v_mul_f32_e32 v8, v8, v92
	v_mul_f32_e32 v4, v4, v92
	s_waitcnt vmcnt(1)
	v_mul_f32_e32 v24, v106, v24
	v_cvt_pk_bf16_f32 v24, v24, v157
	ds_write_b16 v68, v24
	v_mul_f32_e32 v24, v25, v92
	v_mul_f32_e32 v24, v107, v24
	v_cvt_pk_bf16_f32 v24, v24, v157
	ds_write_b16 v68, v24 offset:272
	v_mul_f32_e32 v24, v26, v92
	v_mul_f32_e32 v24, v108, v24
	v_cvt_pk_bf16_f32 v24, v24, v157
	ds_write_b16 v68, v24 offset:544
	v_mul_f32_e32 v24, v27, v92
	v_mul_f32_e32 v24, v109, v24
	v_cvt_pk_bf16_f32 v24, v24, v157
	ds_write_b16 v68, v24 offset:816
	v_mul_f32_e32 v24, v28, v92
	v_mul_f32_e32 v24, v102, v24
	v_cvt_pk_bf16_f32 v24, v24, v157
	ds_write_b16 v68, v24 offset:1088
	v_mul_f32_e32 v24, v29, v92
	v_mul_f32_e32 v24, v103, v24
	v_cvt_pk_bf16_f32 v24, v24, v157
	ds_write_b16 v68, v24 offset:1360
	v_mul_f32_e32 v24, v30, v92
	v_mul_f32_e32 v24, v104, v24
	v_cvt_pk_bf16_f32 v24, v24, v157
	ds_write_b16 v68, v24 offset:1632
	v_mul_f32_e32 v24, v31, v92
	v_mul_f32_e32 v24, v105, v24
	v_cvt_pk_bf16_f32 v24, v24, v157
	ds_write_b16 v68, v24 offset:1904
	v_mul_f32_e32 v24, v32, v92
	v_mul_f32_e32 v24, v98, v24
	v_cvt_pk_bf16_f32 v24, v24, v157
	ds_write_b16 v68, v24 offset:2176
	v_mul_f32_e32 v24, v33, v92
	v_mul_f32_e32 v24, v99, v24
	v_cvt_pk_bf16_f32 v24, v24, v157
	ds_write_b16 v68, v24 offset:2448
	v_mul_f32_e32 v24, v34, v92
	v_mul_f32_e32 v24, v100, v24
	v_cvt_pk_bf16_f32 v24, v24, v157
	ds_write_b16 v68, v24 offset:2720
	v_mul_f32_e32 v24, v35, v92
	v_mul_f32_e32 v24, v101, v24
	v_cvt_pk_bf16_f32 v24, v24, v157
	ds_write_b16 v68, v24 offset:2992
	v_mul_f32_e32 v24, v36, v92
	v_mul_f32_e32 v24, v94, v24
	v_cvt_pk_bf16_f32 v24, v24, v157
	ds_write_b16 v68, v24 offset:3264
	v_mul_f32_e32 v24, v37, v92
	v_mul_f32_e32 v24, v95, v24
	v_cvt_pk_bf16_f32 v24, v24, v157
	ds_write_b16 v68, v24 offset:3536
	v_mul_f32_e32 v24, v38, v92
	v_mul_f32_e32 v24, v96, v24
	v_cvt_pk_bf16_f32 v24, v24, v157
	ds_write_b16 v68, v24 offset:3808
	v_mul_f32_e32 v24, v39, v92
	v_mul_f32_e32 v24, v97, v24
	v_cvt_pk_bf16_f32 v24, v24, v157
	ds_write_b16 v68, v24 offset:4080
	v_mul_f32_e32 v24, v40, v92
	s_waitcnt vmcnt(8)
	v_mul_f32_e32 v24, v128, v24
	v_cvt_pk_bf16_f32 v24, v24, v157
	ds_write_b16 v68, v24 offset:4352
	v_mul_f32_e32 v24, v41, v92
	v_mul_f32_e32 v24, v129, v24
	v_cvt_pk_bf16_f32 v24, v24, v157
	ds_write_b16 v68, v24 offset:4624
	v_mul_f32_e32 v24, v42, v92
	v_mul_f32_e32 v24, v130, v24
	v_cvt_pk_bf16_f32 v24, v24, v157
	ds_write_b16 v68, v24 offset:4896
	v_mul_f32_e32 v24, v43, v92
	v_mul_f32_e32 v24, v131, v24
	v_cvt_pk_bf16_f32 v24, v24, v157
	ds_write_b16 v68, v24 offset:5168
	v_mul_f32_e32 v24, v44, v92
	v_mul_f32_e32 v24, v124, v24
	v_cvt_pk_bf16_f32 v24, v24, v157
	ds_write_b16 v68, v24 offset:5440
	v_mul_f32_e32 v24, v45, v92
	v_mul_f32_e32 v24, v125, v24
	v_cvt_pk_bf16_f32 v24, v24, v157
	ds_write_b16 v68, v24 offset:5712
	v_mul_f32_e32 v24, v46, v92
	v_mul_f32_e32 v24, v126, v24
	v_cvt_pk_bf16_f32 v24, v24, v157
	ds_write_b16 v68, v24 offset:5984
	v_mul_f32_e32 v24, v47, v92
	v_mul_f32_e32 v24, v127, v24
	v_cvt_pk_bf16_f32 v24, v24, v157
	ds_write_b16 v68, v24 offset:6256
	v_mul_f32_e32 v24, v48, v92
	v_mul_f32_e32 v24, v120, v24
	v_cvt_pk_bf16_f32 v24, v24, v157
	ds_write_b16 v68, v24 offset:6528
	v_mul_f32_e32 v24, v49, v92
	v_mul_f32_e32 v24, v121, v24
	v_cvt_pk_bf16_f32 v24, v24, v157
	ds_write_b16 v68, v24 offset:6800
	v_mul_f32_e32 v24, v50, v92
	v_mul_f32_e32 v24, v122, v24
	v_cvt_pk_bf16_f32 v24, v24, v157
	ds_write_b16 v68, v24 offset:7072
	v_mul_f32_e32 v24, v51, v92
	v_mul_f32_e32 v24, v123, v24
	v_cvt_pk_bf16_f32 v24, v24, v157
	ds_write_b16 v68, v24 offset:7344
	v_mul_f32_e32 v24, v52, v92
	v_mul_f32_e32 v24, v110, v24
	v_cvt_pk_bf16_f32 v24, v24, v157
	ds_write_b16 v68, v24 offset:7616
	v_mul_f32_e32 v24, v53, v92
	v_mul_f32_e32 v24, v111, v24
	v_cvt_pk_bf16_f32 v24, v24, v157
	ds_write_b16 v68, v24 offset:7888
	v_mul_f32_e32 v24, v54, v92
	v_mul_f32_e32 v24, v112, v24
	v_cvt_pk_bf16_f32 v24, v24, v157
	ds_write_b16 v68, v24 offset:8160
	v_mul_f32_e32 v24, v55, v92
	v_mul_f32_e32 v24, v113, v24
	v_cvt_pk_bf16_f32 v24, v24, v157
	ds_write_b16 v68, v24 offset:8432
	v_mul_f32_e32 v24, v56, v92
	s_waitcnt vmcnt(4)
	v_mul_f32_e32 v24, v144, v24
	v_cvt_pk_bf16_f32 v24, v24, v157
	ds_write_b16 v68, v24 offset:8704
	v_mul_f32_e32 v24, v57, v92
	v_mul_f32_e32 v24, v145, v24
	v_cvt_pk_bf16_f32 v24, v24, v157
	ds_write_b16 v68, v24 offset:8976
	v_mul_f32_e32 v24, v58, v92
	v_mul_f32_e32 v24, v146, v24
	v_cvt_pk_bf16_f32 v24, v24, v157
	ds_write_b16 v68, v24 offset:9248
	v_mul_f32_e32 v24, v59, v92
	v_mul_f32_e32 v24, v147, v24
	v_cvt_pk_bf16_f32 v24, v24, v157
	ds_write_b16 v68, v24 offset:9520
	v_mul_f32_e32 v24, v60, v92
	v_mul_f32_e32 v24, v140, v24
	v_cvt_pk_bf16_f32 v24, v24, v157
	ds_write_b16 v68, v24 offset:9792
	v_mul_f32_e32 v24, v61, v92
	v_mul_f32_e32 v24, v141, v24
	v_cvt_pk_bf16_f32 v24, v24, v157
	ds_write_b16 v68, v24 offset:10064
	v_mul_f32_e32 v24, v62, v92
	v_mul_f32_e32 v24, v142, v24
	v_cvt_pk_bf16_f32 v24, v24, v157
	ds_write_b16 v68, v24 offset:10336
	v_mul_f32_e32 v24, v63, v92
	v_mul_f32_e32 v24, v143, v24
	v_cvt_pk_bf16_f32 v24, v24, v157
	ds_write_b16 v68, v24 offset:10608
	v_mul_f32_e32 v24, v88, v92
	v_mul_f32_e32 v24, v136, v24
	v_cvt_pk_bf16_f32 v24, v24, v157
	ds_write_b16 v68, v24 offset:10880
	v_mul_f32_e32 v24, v89, v92
	v_mul_f32_e32 v24, v137, v24
	v_cvt_pk_bf16_f32 v24, v24, v157
	ds_write_b16 v68, v24 offset:11152
	v_mul_f32_e32 v24, v90, v92
	v_mul_f32_e32 v24, v138, v24
	v_cvt_pk_bf16_f32 v24, v24, v157
	ds_write_b16 v68, v24 offset:11424
	v_mul_f32_e32 v24, v91, v92
	v_mul_f32_e32 v24, v139, v24
	v_mul_f32_e32 v8, v132, v8
	v_cvt_pk_bf16_f32 v24, v24, v157
	ds_write_b16 v68, v24 offset:11696
	v_cvt_pk_bf16_f32 v8, v8, v157
	ds_write_b16 v68, v8 offset:11968
	v_mul_f32_e32 v8, v10, v92
	v_mul_f32_e32 v8, v133, v8
	v_cvt_pk_bf16_f32 v8, v8, v157
	ds_write_b16 v68, v8 offset:12240
	v_mul_f32_e32 v8, v9, v92
	v_mul_f32_e32 v8, v134, v8
	v_cvt_pk_bf16_f32 v8, v8, v157
	ds_write_b16 v68, v8 offset:12512
	v_mul_f32_e32 v8, v11, v92
	v_mul_f32_e32 v8, v135, v8
	s_waitcnt vmcnt(0)
	v_mul_f32_e32 v4, v162, v4
	v_cvt_pk_bf16_f32 v8, v8, v157
	ds_write_b16 v68, v8 offset:12784
	v_cvt_pk_bf16_f32 v4, v4, v157
	ds_write_b16 v68, v4 offset:13056
	v_mul_f32_e32 v4, v12, v92
	v_mul_f32_e32 v4, v163, v4
	v_cvt_pk_bf16_f32 v4, v4, v157
	ds_write_b16 v68, v4 offset:13328
	v_mul_f32_e32 v4, v5, v92
	v_mul_f32_e32 v4, v164, v4
	v_cvt_pk_bf16_f32 v4, v4, v157
	ds_write_b16 v68, v4 offset:13600
	v_mul_f32_e32 v4, v13, v92
	v_mul_f32_e32 v4, v165, v4
	v_cvt_pk_bf16_f32 v4, v4, v157
	ds_write_b16 v68, v4 offset:13872
	v_mul_f32_e32 v4, v6, v92
	v_mul_f32_e32 v4, v152, v4
	v_cvt_pk_bf16_f32 v4, v4, v157
	ds_write_b16 v68, v4 offset:14144
	v_mul_f32_e32 v4, v14, v92
	v_mul_f32_e32 v4, v153, v4
	v_cvt_pk_bf16_f32 v4, v4, v157
	ds_write_b16 v68, v4 offset:14416
	v_mul_f32_e32 v4, v7, v92
	v_mul_f32_e32 v4, v154, v4
	v_cvt_pk_bf16_f32 v4, v4, v157
	ds_write_b16 v68, v4 offset:14688
	v_mul_f32_e32 v4, v15, v92
	v_mul_f32_e32 v4, v155, v4
	v_cvt_pk_bf16_f32 v4, v4, v157
	ds_write_b16 v68, v4 offset:14960
	v_mul_f32_e32 v4, v16, v92
	v_mul_f32_e32 v4, v148, v4
	v_cvt_pk_bf16_f32 v4, v4, v157
	ds_write_b16 v68, v4 offset:15232
	v_mul_f32_e32 v4, v18, v92
	v_mul_f32_e32 v4, v149, v4
	v_cvt_pk_bf16_f32 v4, v4, v157
	ds_write_b16 v68, v4 offset:15504
	v_mul_f32_e32 v4, v17, v92
	v_mul_f32_e32 v4, v150, v4
	v_cvt_pk_bf16_f32 v4, v4, v157
	ds_write_b16 v68, v4 offset:15776
	v_mul_f32_e32 v4, v19, v92
	v_mul_f32_e32 v4, v151, v4
	v_cvt_pk_bf16_f32 v4, v4, v157
	ds_write_b16 v68, v4 offset:16048
	v_mul_f32_e32 v4, v20, v92
	v_mul_f32_e32 v0, v0, v4
	v_cvt_pk_bf16_f32 v0, v0, v157
	ds_write_b16 v68, v0 offset:16320
	v_mul_f32_e32 v0, v22, v92
	v_mul_f32_e32 v0, v1, v0
	v_cvt_pk_bf16_f32 v0, v0, v157
	ds_write_b16 v68, v0 offset:16592
	v_mul_f32_e32 v0, v21, v92
	v_mul_f32_e32 v0, v2, v0
	v_cvt_pk_bf16_f32 v0, v0, v157
	ds_write_b16 v68, v0 offset:16864
	v_mul_f32_e32 v0, v23, v92
	v_mul_f32_e32 v0, v3, v0
	v_cvt_pk_bf16_f32 v0, v0, v157
	ds_write_b16 v69, v0
	s_waitcnt lgkmcnt(0)
	s_barrier
	global_load_dwordx4 v[0:3], v[70:71], off
	global_load_dwordx4 v[4:7], v[72:73], off
	global_load_dwordx4 v[8:11], v[74:75], off
	global_load_dwordx4 v[12:15], v[76:77], off
	global_load_dwordx4 v[16:19], v[70:71], off offset:64
	global_load_dwordx4 v[20:23], v[72:73], off offset:64
	global_load_dwordx4 v[24:27], v[74:75], off offset:64
	global_load_dwordx4 v[28:31], v[76:77], off offset:64
	global_load_dwordx4 v[32:35], v[70:71], off offset:128
	global_load_dwordx4 v[36:39], v[72:73], off offset:128
	global_load_dwordx4 v[40:43], v[74:75], off offset:128
	global_load_dwordx4 v[44:47], v[76:77], off offset:128
	global_load_dwordx4 v[48:51], v[70:71], off offset:192
	global_load_dwordx4 v[88:91], v[72:73], off offset:192
	global_load_dwordx4 v[92:95], v[74:75], off offset:192
	global_load_dwordx4 v[96:99], v[76:77], off offset:192
	ds_read_b128 v[52:55], v119
	ds_read_b128 v[56:59], v119 offset:4352
	ds_read_b128 v[60:63], v119 offset:8704
	ds_read_b128 v[100:103], v119 offset:13056
	s_waitcnt vmcnt(15) lgkmcnt(3)
	v_mfma_f32_16x16x32_bf16 v[104:107], v[52:55], v[0:3], 0
	s_waitcnt lgkmcnt(2)
	v_mfma_f32_16x16x32_bf16 v[108:111], v[56:59], v[0:3], 0
	s_waitcnt lgkmcnt(1)
	v_mfma_f32_16x16x32_bf16 v[112:115], v[60:63], v[0:3], 0
	s_waitcnt lgkmcnt(0)
	v_mfma_f32_16x16x32_bf16 v[0:3], v[100:103], v[0:3], 0
	s_waitcnt vmcnt(14)
	v_mfma_f32_16x16x32_bf16 v[120:123], v[52:55], v[4:7], 0
	v_mfma_f32_16x16x32_bf16 v[124:127], v[56:59], v[4:7], 0
	v_mfma_f32_16x16x32_bf16 v[128:131], v[60:63], v[4:7], 0
	v_mfma_f32_16x16x32_bf16 v[4:7], v[100:103], v[4:7], 0
	s_waitcnt vmcnt(13)
	v_mfma_f32_16x16x32_bf16 v[132:135], v[52:55], v[8:11], 0
	v_mfma_f32_16x16x32_bf16 v[136:139], v[56:59], v[8:11], 0
	v_mfma_f32_16x16x32_bf16 v[140:143], v[60:63], v[8:11], 0
	v_mfma_f32_16x16x32_bf16 v[8:11], v[100:103], v[8:11], 0
	s_waitcnt vmcnt(12)
	v_mfma_f32_16x16x32_bf16 v[52:55], v[52:55], v[12:15], 0
	v_mfma_f32_16x16x32_bf16 v[56:59], v[56:59], v[12:15], 0
	v_mfma_f32_16x16x32_bf16 v[60:63], v[60:63], v[12:15], 0
	v_mfma_f32_16x16x32_bf16 v[12:15], v[100:103], v[12:15], 0
	ds_read_b128 v[100:103], v119 offset:64
	ds_read_b128 v[144:147], v119 offset:4416
	ds_read_b128 v[148:151], v119 offset:8768
	ds_read_b128 v[152:155], v119 offset:13120
	s_waitcnt vmcnt(11) lgkmcnt(3)
	v_mfma_f32_16x16x32_bf16 v[104:107], v[100:103], v[16:19], v[104:107]
	s_waitcnt lgkmcnt(2)
	v_mfma_f32_16x16x32_bf16 v[108:111], v[144:147], v[16:19], v[108:111]
	s_waitcnt lgkmcnt(1)
	v_mfma_f32_16x16x32_bf16 v[112:115], v[148:151], v[16:19], v[112:115]
	s_waitcnt lgkmcnt(0)
	v_mfma_f32_16x16x32_bf16 v[0:3], v[152:155], v[16:19], v[0:3]
	s_waitcnt vmcnt(10)
	v_mfma_f32_16x16x32_bf16 v[16:19], v[100:103], v[20:23], v[120:123]
	v_mfma_f32_16x16x32_bf16 v[120:123], v[144:147], v[20:23], v[124:127]
	v_mfma_f32_16x16x32_bf16 v[124:127], v[148:151], v[20:23], v[128:131]
	v_mfma_f32_16x16x32_bf16 v[4:7], v[152:155], v[20:23], v[4:7]
	s_waitcnt vmcnt(9)
	v_mfma_f32_16x16x32_bf16 v[20:23], v[100:103], v[24:27], v[132:135]
	v_mfma_f32_16x16x32_bf16 v[128:131], v[144:147], v[24:27], v[136:139]
	v_mfma_f32_16x16x32_bf16 v[132:135], v[148:151], v[24:27], v[140:143]
	v_mfma_f32_16x16x32_bf16 v[8:11], v[152:155], v[24:27], v[8:11]
	s_waitcnt vmcnt(8)
	v_mfma_f32_16x16x32_bf16 v[24:27], v[100:103], v[28:31], v[52:55]
	v_mfma_f32_16x16x32_bf16 v[52:55], v[144:147], v[28:31], v[56:59]
	v_mfma_f32_16x16x32_bf16 v[56:59], v[148:151], v[28:31], v[60:63]
	v_mfma_f32_16x16x32_bf16 v[12:15], v[152:155], v[28:31], v[12:15]
	ds_read_b128 v[28:31], v119 offset:128
	s_nop 0
	ds_read_b128 v[60:63], v119 offset:4480
	ds_read_b128 v[100:103], v119 offset:8832
	ds_read_b128 v[136:139], v119 offset:13184
	s_waitcnt vmcnt(7) lgkmcnt(3)
	v_mfma_f32_16x16x32_bf16 v[104:107], v[28:31], v[32:35], v[104:107]
	s_waitcnt lgkmcnt(2)
	v_mfma_f32_16x16x32_bf16 v[108:111], v[60:63], v[32:35], v[108:111]
	s_waitcnt lgkmcnt(1)
	v_mfma_f32_16x16x32_bf16 v[112:115], v[100:103], v[32:35], v[112:115]
	s_waitcnt lgkmcnt(0)
	v_mfma_f32_16x16x32_bf16 v[0:3], v[136:139], v[32:35], v[0:3]
	s_waitcnt vmcnt(6)
	v_mfma_f32_16x16x32_bf16 v[32:35], v[60:63], v[36:39], v[120:123]
	v_mfma_f32_16x16x32_bf16 v[120:123], v[100:103], v[36:39], v[124:127]
	v_mfma_f32_16x16x32_bf16 v[4:7], v[136:139], v[36:39], v[4:7]
	s_waitcnt vmcnt(5)
	v_mfma_f32_16x16x32_bf16 v[124:127], v[60:63], v[40:43], v[128:131]
	v_mfma_f32_16x16x32_bf16 v[8:11], v[136:139], v[40:43], v[8:11]
	s_waitcnt vmcnt(4)
	v_mfma_f32_16x16x32_bf16 v[136:139], v[136:139], v[44:47], v[12:15]
	s_nop 2
	ds_read_b128 v[12:15], v119 offset:192
	ds_read_b128 v[144:147], v119 offset:4544
	ds_read_b128 v[148:151], v119 offset:8896
	ds_read_b128 v[152:155], v119 offset:13248
	v_mfma_f32_16x16x32_bf16 v[16:19], v[28:31], v[36:39], v[16:19]
	v_mfma_f32_16x16x32_bf16 v[20:23], v[28:31], v[40:43], v[20:23]
	v_mfma_f32_16x16x32_bf16 v[128:131], v[100:103], v[40:43], v[132:135]
	v_mfma_f32_16x16x32_bf16 v[132:135], v[28:31], v[44:47], v[24:27]
	s_waitcnt vmcnt(1) lgkmcnt(2)
	v_mfma_f32_16x16x32_bf16 v[24:27], v[144:147], v[92:95], v[124:127]
	s_nop 2
	v_add_u32_e32 v124, s3, v118
	v_mfma_f32_16x16x32_bf16 v[140:143], v[60:63], v[44:47], v[52:55]
	v_ashrrev_i32_e32 v125, 31, v124
	s_add_i32 s3, s3, s6
	s_cmp_lt_i32 s7, s2
	v_mfma_f32_16x16x32_bf16 v[100:103], v[100:103], v[44:47], v[56:59]
	v_mfma_f32_16x16x32_bf16 v[44:47], v[12:15], v[88:91], v[16:19]
	v_mfma_f32_16x16x32_bf16 v[40:43], v[144:147], v[88:91], v[32:35]
	s_waitcnt lgkmcnt(1)
	v_mfma_f32_16x16x32_bf16 v[36:39], v[148:151], v[88:91], v[120:123]
	s_waitcnt lgkmcnt(0)
	v_mfma_f32_16x16x32_bf16 v[32:35], v[152:155], v[88:91], v[4:7]
	v_mad_i64_i32 v[88:89], s[24:25], v124, s9, v[84:85]
	global_load_dword v120, v[78:79], off
	v_mfma_f32_16x16x32_bf16 v[60:63], v[12:15], v[48:51], v[104:107]
	v_mfma_f32_16x16x32_bf16 v[28:31], v[12:15], v[92:95], v[20:23]
	s_nop 1
	v_add_u32_e32 v106, 32, v124
	v_ashrrev_i32_e32 v107, 31, v106
	s_waitcnt vmcnt(0)
	s_nop 1
	v_add_f32_e32 v60, v60, v120
	v_mfma_f32_16x16x32_bf16 v[20:23], v[148:151], v[92:95], v[128:131]
	v_add_f32_e32 v61, v61, v120
	v_add_f32_e32 v62, v62, v120
	v_add_f32_e32 v63, v63, v120
	v_mfma_f32_16x16x32_bf16 v[12:15], v[12:15], v[96:99], v[132:135]
	global_load_dwordx2 v[126:127], v[88:89], off offset:704
	global_load_dwordx2 v[128:129], v[88:89], off offset:736
	global_load_dwordx2 v[130:131], v[88:89], off offset:768
	global_load_dwordx2 v[132:133], v[88:89], off offset:800
	global_load_dword v123, v[80:81], off offset:64
	v_add_u32_e32 v134, 16, v124
	v_mad_i64_i32 v[88:89], s[24:25], v134, s9, v[84:85]
	v_mfma_f32_16x16x32_bf16 v[56:59], v[144:147], v[48:51], v[108:111]
	v_ashrrev_i32_e32 v135, 31, v134
	s_waitcnt vmcnt(0)
	v_add_f32_e32 v44, v44, v123
	v_mfma_f32_16x16x32_bf16 v[52:55], v[148:151], v[48:51], v[112:115]
	s_nop 2
	global_load_dwordx2 v[114:115], v[88:89], off offset:704
	global_load_dwordx2 v[112:113], v[88:89], off offset:736
	global_load_dwordx2 v[110:111], v[88:89], off offset:768
	global_load_dwordx2 v[108:109], v[88:89], off offset:800
	global_load_dword v122, v[80:81], off offset:128
	v_mad_i64_i32 v[88:89], s[24:25], v106, s9, v[84:85]
	v_mfma_f32_16x16x32_bf16 v[48:51], v[152:155], v[48:51], v[0:3]
	v_add_f32_e32 v56, v56, v120
	v_add_f32_e32 v57, v57, v120
	v_add_f32_e32 v58, v58, v120
	v_mfma_f32_16x16x32_bf16 v[0:3], v[152:155], v[96:99], v[136:139]
	v_add_f32_e32 v59, v59, v120
	v_add_f32_e32 v52, v52, v120
	v_add_f32_e32 v53, v53, v120
	v_lshlrev_b32_e32 v136, 16, v126
	v_mul_f32_e32 v137, 0x3d372713, v136
	v_mul_f32_e32 v137, v137, v136
	v_fma_f32 v137, v137, v136, v136
	v_mul_f32_e32 v137, 0x3f4c422a, v137
	v_mul_f32_e32 v137, -2.0, v137
	v_mul_f32_e32 v137, 0x3fb8aa3b, v137
	v_exp_f32_e32 v137, v137
	v_and_b32_e32 v126, 0xffff0000, v126
	v_mfma_f32_16x16x32_bf16 v[16:19], v[152:155], v[92:95], v[8:11]
	v_add_f32_e32 v54, v54, v120
	v_add_f32_e32 v137, 1.0, v137
	v_rcp_f32_e32 v137, v137
	v_mfma_f32_16x16x32_bf16 v[8:11], v[144:147], v[96:99], v[140:143]
	v_add_f32_e32 v55, v55, v120
	v_add_f32_e32 v48, v48, v120
	v_mul_f32_e32 v136, v137, v136
	v_mul_f32_e32 v60, v60, v136
	v_mul_f32_e32 v136, 0x3d372713, v126
	v_mul_f32_e32 v136, v136, v126
	v_fma_f32 v136, v136, v126, v126
	v_mul_f32_e32 v136, 0x3f4c422a, v136
	v_mul_f32_e32 v136, -2.0, v136
	v_mul_f32_e32 v136, 0x3fb8aa3b, v136
	v_exp_f32_e32 v136, v136
	v_mfma_f32_16x16x32_bf16 v[4:7], v[148:151], v[96:99], v[100:103]
	v_add_u32_e32 v96, 48, v124
	global_load_dwordx2 v[104:105], v[88:89], off offset:704
	s_nop 0
	global_load_dwordx2 v[102:103], v[88:89], off offset:736
	global_load_dwordx2 v[100:101], v[88:89], off offset:768
	global_load_dwordx2 v[98:99], v[88:89], off offset:800
	global_load_dword v121, v[80:81], off offset:192
	v_add_f32_e32 v136, 1.0, v136
	v_rcp_f32_e32 v136, v136
	v_mad_i64_i32 v[88:89], s[24:25], v96, s9, v[84:85]
	global_load_dwordx2 v[94:95], v[88:89], off offset:704
	global_load_dwordx2 v[92:93], v[88:89], off offset:736
	global_load_dwordx2 v[90:91], v[88:89], off offset:768
	s_nop 0
	global_load_dwordx2 v[88:89], v[88:89], off offset:800
	v_mul_f32_e32 v126, v136, v126
	v_mul_f32_e32 v61, v61, v126
	v_cvt_pk_bf16_f32 v60, v60, v61
	v_lshlrev_b32_e32 v61, 16, v127
	v_mul_f32_e32 v126, 0x3d372713, v61
	v_mul_f32_e32 v126, v126, v61
	v_fma_f32 v126, v126, v61, v61
	v_mul_f32_e32 v126, 0x3f4c422a, v126
	v_mul_f32_e32 v126, -2.0, v126
	v_mul_f32_e32 v126, 0x3fb8aa3b, v126
	v_exp_f32_e32 v126, v126
	v_lshlrev_b64 v[124:125], 11, v[124:125]
	v_add_f32_e32 v49, v49, v120
	v_add_f32_e32 v50, v50, v120
	v_add_f32_e32 v126, 1.0, v126
	v_rcp_f32_e32 v126, v126
	v_add_f32_e32 v51, v51, v120
	v_add_f32_e32 v45, v45, v123
	v_add_f32_e32 v46, v46, v123
	v_mul_f32_e32 v61, v126, v61
	v_mul_f32_e32 v61, v62, v61
	v_and_b32_e32 v62, 0xffff0000, v127
	v_mul_f32_e32 v126, 0x3d372713, v62
	v_mul_f32_e32 v126, v126, v62
	v_fma_f32 v126, v126, v62, v62
	v_mul_f32_e32 v126, 0x3f4c422a, v126
	v_mul_f32_e32 v126, -2.0, v126
	v_mul_f32_e32 v126, 0x3fb8aa3b, v126
	v_exp_f32_e32 v126, v126
	v_add_f32_e32 v47, v47, v123
	v_add_f32_e32 v40, v40, v123
	v_add_f32_e32 v41, v41, v123
	v_add_f32_e32 v126, 1.0, v126
	v_rcp_f32_e32 v126, v126
	v_add_f32_e32 v42, v42, v123
	v_add_f32_e32 v43, v43, v123
	v_add_f32_e32 v36, v36, v123
	v_mul_f32_e32 v62, v126, v62
	v_mul_f32_e32 v62, v63, v62
	v_cvt_pk_bf16_f32 v61, v61, v62
	v_lshl_add_u64 v[62:63], v[86:87], 0, v[124:125]
	global_store_dwordx2 v[62:63], v[60:61], off offset:1024
	v_lshlrev_b32_e32 v60, 16, v128
	v_mul_f32_e32 v61, 0x3d372713, v60
	v_mul_f32_e32 v61, v61, v60
	v_fma_f32 v61, v61, v60, v60
	v_mul_f32_e32 v61, 0x3f4c422a, v61
	v_mul_f32_e32 v61, -2.0, v61
	v_mul_f32_e32 v61, 0x3fb8aa3b, v61
	v_exp_f32_e32 v61, v61
	v_add_f32_e32 v37, v37, v123
	v_add_f32_e32 v38, v38, v123
	v_add_f32_e32 v39, v39, v123
	v_add_f32_e32 v61, 1.0, v61
	v_rcp_f32_e32 v61, v61
	v_add_f32_e32 v32, v32, v123
	v_add_f32_e32 v33, v33, v123
	v_add_f32_e32 v34, v34, v123
	v_mul_f32_e32 v60, v61, v60
	v_mul_f32_e32 v56, v56, v60
	v_and_b32_e32 v60, 0xffff0000, v128
	v_mul_f32_e32 v61, 0x3d372713, v60
	v_mul_f32_e32 v61, v61, v60
	v_fma_f32 v61, v61, v60, v60
	v_mul_f32_e32 v61, 0x3f4c422a, v61
	v_mul_f32_e32 v61, -2.0, v61
	v_mul_f32_e32 v61, 0x3fb8aa3b, v61
	v_exp_f32_e32 v61, v61
	v_add_f32_e32 v35, v35, v123
	s_waitcnt vmcnt(10)
	v_add_f32_e32 v28, v28, v122
	v_add_f32_e32 v29, v29, v122
	v_add_f32_e32 v61, 1.0, v61
	v_rcp_f32_e32 v61, v61
	v_add_f32_e32 v30, v30, v122
	v_add_f32_e32 v31, v31, v122
	v_add_f32_e32 v24, v24, v122
	v_mul_f32_e32 v60, v61, v60
	v_mul_f32_e32 v57, v57, v60
	v_cvt_pk_bf16_f32 v56, v56, v57
	v_lshlrev_b32_e32 v57, 16, v129
	v_mul_f32_e32 v60, 0x3d372713, v57
	v_mul_f32_e32 v60, v60, v57
	v_fma_f32 v60, v60, v57, v57
	v_mul_f32_e32 v60, 0x3f4c422a, v60
	v_mul_f32_e32 v60, -2.0, v60
	v_mul_f32_e32 v60, 0x3fb8aa3b, v60
	v_exp_f32_e32 v60, v60
	v_add_f32_e32 v25, v25, v122
	v_add_f32_e32 v26, v26, v122
	v_add_f32_e32 v27, v27, v122
	v_add_f32_e32 v60, 1.0, v60
	v_rcp_f32_e32 v60, v60
	v_add_f32_e32 v20, v20, v122
	v_add_f32_e32 v21, v21, v122
	v_add_f32_e32 v22, v22, v122
	v_mul_f32_e32 v57, v60, v57
	v_mul_f32_e32 v57, v58, v57
	v_and_b32_e32 v58, 0xffff0000, v129
	v_mul_f32_e32 v60, 0x3d372713, v58
	v_mul_f32_e32 v60, v60, v58
	v_fma_f32 v60, v60, v58, v58
	v_mul_f32_e32 v60, 0x3f4c422a, v60
	v_mul_f32_e32 v60, -2.0, v60
	v_mul_f32_e32 v60, 0x3fb8aa3b, v60
	v_exp_f32_e32 v60, v60
	v_add_f32_e32 v23, v23, v122
	v_add_f32_e32 v16, v16, v122
	v_add_f32_e32 v17, v17, v122
	v_add_f32_e32 v60, 1.0, v60
	v_rcp_f32_e32 v60, v60
	v_add_f32_e32 v18, v18, v122
	v_add_f32_e32 v19, v19, v122
	s_waitcnt vmcnt(5)
	v_add_f32_e32 v12, v12, v121
	v_mul_f32_e32 v58, v60, v58
	v_mul_f32_e32 v58, v59, v58
	v_cvt_pk_bf16_f32 v57, v57, v58
	global_store_dwordx2 v[62:63], v[56:57], off offset:1056
	v_lshlrev_b32_e32 v56, 16, v130
	v_mul_f32_e32 v57, 0x3d372713, v56
	v_mul_f32_e32 v57, v57, v56
	v_fma_f32 v57, v57, v56, v56
	v_mul_f32_e32 v57, 0x3f4c422a, v57
	v_mul_f32_e32 v57, -2.0, v57
	v_mul_f32_e32 v57, 0x3fb8aa3b, v57
	v_exp_f32_e32 v57, v57
	v_add_f32_e32 v13, v13, v121
	v_add_f32_e32 v14, v14, v121
	v_ashrrev_i32_e32 v97, 31, v96
	v_add_f32_e32 v57, 1.0, v57
	v_rcp_f32_e32 v57, v57
	v_add_f32_e32 v15, v15, v121
	v_add_f32_e32 v8, v8, v121
	v_add_f32_e32 v9, v9, v121
	v_mul_f32_e32 v56, v57, v56
	v_mul_f32_e32 v52, v52, v56
	v_and_b32_e32 v56, 0xffff0000, v130
	v_mul_f32_e32 v57, 0x3d372713, v56
	v_mul_f32_e32 v57, v57, v56
	v_fma_f32 v57, v57, v56, v56
	v_mul_f32_e32 v57, 0x3f4c422a, v57
	v_mul_f32_e32 v57, -2.0, v57
	v_mul_f32_e32 v57, 0x3fb8aa3b, v57
	v_exp_f32_e32 v57, v57
	v_add_f32_e32 v10, v10, v121
	v_add_f32_e32 v11, v11, v121
	v_add_f32_e32 v4, v4, v121
	v_add_f32_e32 v57, 1.0, v57
	v_rcp_f32_e32 v57, v57
	v_add_f32_e32 v5, v5, v121
	v_add_f32_e32 v6, v6, v121
	v_add_f32_e32 v7, v7, v121
	v_mul_f32_e32 v56, v57, v56
	v_mul_f32_e32 v53, v53, v56
	v_cvt_pk_bf16_f32 v52, v52, v53
	v_lshlrev_b32_e32 v53, 16, v131
	v_mul_f32_e32 v56, 0x3d372713, v53
	v_mul_f32_e32 v56, v56, v53
	v_fma_f32 v56, v56, v53, v53
	v_mul_f32_e32 v56, 0x3f4c422a, v56
	v_mul_f32_e32 v56, -2.0, v56
	v_mul_f32_e32 v56, 0x3fb8aa3b, v56
	v_exp_f32_e32 v56, v56
	v_add_f32_e32 v0, v0, v121
	v_add_f32_e32 v1, v1, v121
	v_add_f32_e32 v2, v2, v121
	v_add_f32_e32 v56, 1.0, v56
	v_rcp_f32_e32 v56, v56
	v_add_f32_e32 v3, v3, v121
	v_mul_f32_e32 v53, v56, v53
	v_mul_f32_e32 v53, v54, v53
	v_and_b32_e32 v54, 0xffff0000, v131
	v_mul_f32_e32 v56, 0x3d372713, v54
	v_mul_f32_e32 v56, v56, v54
	v_fma_f32 v56, v56, v54, v54
	v_mul_f32_e32 v56, 0x3f4c422a, v56
	v_mul_f32_e32 v56, -2.0, v56
	v_mul_f32_e32 v56, 0x3fb8aa3b, v56
	v_exp_f32_e32 v56, v56
	s_nop 0
	v_add_f32_e32 v56, 1.0, v56
	v_rcp_f32_e32 v56, v56
	s_nop 0
	v_mul_f32_e32 v54, v56, v54
	v_mul_f32_e32 v54, v55, v54
	v_cvt_pk_bf16_f32 v53, v53, v54
	global_store_dwordx2 v[62:63], v[52:53], off offset:1088
	v_lshlrev_b32_e32 v52, 16, v132
	v_mul_f32_e32 v53, 0x3d372713, v52
	v_mul_f32_e32 v53, v53, v52
	v_fma_f32 v53, v53, v52, v52
	v_mul_f32_e32 v53, 0x3f4c422a, v53
	v_mul_f32_e32 v53, -2.0, v53
	v_mul_f32_e32 v53, 0x3fb8aa3b, v53
	v_exp_f32_e32 v53, v53
	s_nop 0
	v_add_f32_e32 v53, 1.0, v53
	v_rcp_f32_e32 v53, v53
	s_nop 0
	v_mul_f32_e32 v52, v53, v52
	v_mul_f32_e32 v48, v48, v52
	v_and_b32_e32 v52, 0xffff0000, v132
	v_mul_f32_e32 v53, 0x3d372713, v52
	v_mul_f32_e32 v53, v53, v52
	v_fma_f32 v53, v53, v52, v52
	v_mul_f32_e32 v53, 0x3f4c422a, v53
	v_mul_f32_e32 v53, -2.0, v53
	v_mul_f32_e32 v53, 0x3fb8aa3b, v53
	v_exp_f32_e32 v53, v53
	s_nop 0
	v_add_f32_e32 v53, 1.0, v53
	v_rcp_f32_e32 v53, v53
	s_nop 0
	v_mul_f32_e32 v52, v53, v52
	v_mul_f32_e32 v49, v49, v52
	v_cvt_pk_bf16_f32 v48, v48, v49
	v_lshlrev_b32_e32 v49, 16, v133
	v_mul_f32_e32 v52, 0x3d372713, v49
	v_mul_f32_e32 v52, v52, v49
	v_fma_f32 v52, v52, v49, v49
	v_mul_f32_e32 v52, 0x3f4c422a, v52
	v_mul_f32_e32 v52, -2.0, v52
	v_mul_f32_e32 v52, 0x3fb8aa3b, v52
	v_exp_f32_e32 v52, v52
	s_nop 0
	v_add_f32_e32 v52, 1.0, v52
	v_rcp_f32_e32 v52, v52
	s_nop 0
	v_mul_f32_e32 v49, v52, v49
	v_mul_f32_e32 v49, v50, v49
	v_and_b32_e32 v50, 0xffff0000, v133
	v_mul_f32_e32 v52, 0x3d372713, v50
	v_mul_f32_e32 v52, v52, v50
	v_fma_f32 v52, v52, v50, v50
	v_mul_f32_e32 v52, 0x3f4c422a, v52
	v_mul_f32_e32 v52, -2.0, v52
	v_mul_f32_e32 v52, 0x3fb8aa3b, v52
	v_exp_f32_e32 v52, v52
	s_nop 0
	v_add_f32_e32 v52, 1.0, v52
	v_rcp_f32_e32 v52, v52
	s_nop 0
	v_mul_f32_e32 v50, v52, v50
	v_mul_f32_e32 v50, v51, v50
	v_cvt_pk_bf16_f32 v49, v49, v50
	v_lshlrev_b32_e32 v50, 16, v114
	v_mul_f32_e32 v51, 0x3d372713, v50
	v_mul_f32_e32 v51, v51, v50
	v_fma_f32 v51, v51, v50, v50
	v_mul_f32_e32 v51, 0x3f4c422a, v51
	v_mul_f32_e32 v51, -2.0, v51
	v_mul_f32_e32 v51, 0x3fb8aa3b, v51
	v_exp_f32_e32 v51, v51
	global_store_dwordx2 v[62:63], v[48:49], off offset:1120
	v_lshlrev_b64 v[48:49], 11, v[134:135]
	v_add_f32_e32 v51, 1.0, v51
	v_rcp_f32_e32 v51, v51
	s_nop 0
	v_mul_f32_e32 v50, v51, v50
	v_mul_f32_e32 v44, v44, v50
	v_and_b32_e32 v50, 0xffff0000, v114
	v_mul_f32_e32 v51, 0x3d372713, v50
	v_mul_f32_e32 v51, v51, v50
	v_fma_f32 v51, v51, v50, v50
	v_mul_f32_e32 v51, 0x3f4c422a, v51
	v_mul_f32_e32 v51, -2.0, v51
	v_mul_f32_e32 v51, 0x3fb8aa3b, v51
	v_exp_f32_e32 v51, v51
	s_nop 0
	v_add_f32_e32 v51, 1.0, v51
	v_rcp_f32_e32 v51, v51
	s_nop 0
	v_mul_f32_e32 v50, v51, v50
	v_mul_f32_e32 v45, v45, v50
	v_cvt_pk_bf16_f32 v44, v44, v45
	v_lshlrev_b32_e32 v45, 16, v115
	v_mul_f32_e32 v50, 0x3d372713, v45
	v_mul_f32_e32 v50, v50, v45
	v_fma_f32 v50, v50, v45, v45
	v_mul_f32_e32 v50, 0x3f4c422a, v50
	v_mul_f32_e32 v50, -2.0, v50
	v_mul_f32_e32 v50, 0x3fb8aa3b, v50
	v_exp_f32_e32 v50, v50
	s_nop 0
	v_add_f32_e32 v50, 1.0, v50
	v_rcp_f32_e32 v50, v50
	s_nop 0
	v_mul_f32_e32 v45, v50, v45
	v_mul_f32_e32 v45, v46, v45
	v_and_b32_e32 v46, 0xffff0000, v115
	v_mul_f32_e32 v50, 0x3d372713, v46
	v_mul_f32_e32 v50, v50, v46
	v_fma_f32 v50, v50, v46, v46
	v_mul_f32_e32 v50, 0x3f4c422a, v50
	v_mul_f32_e32 v50, -2.0, v50
	v_mul_f32_e32 v50, 0x3fb8aa3b, v50
	v_exp_f32_e32 v50, v50
	s_nop 0
	v_add_f32_e32 v50, 1.0, v50
	v_rcp_f32_e32 v50, v50
	s_nop 0
	v_mul_f32_e32 v46, v50, v46
	v_mul_f32_e32 v46, v47, v46
	v_cvt_pk_bf16_f32 v45, v45, v46
	v_lshl_add_u64 v[46:47], v[86:87], 0, v[48:49]
	global_store_dwordx2 v[46:47], v[44:45], off offset:1024
	v_lshlrev_b32_e32 v44, 16, v112
	v_mul_f32_e32 v45, 0x3d372713, v44
	v_mul_f32_e32 v45, v45, v44
	v_fma_f32 v45, v45, v44, v44
	v_mul_f32_e32 v45, 0x3f4c422a, v45
	v_mul_f32_e32 v45, -2.0, v45
	v_mul_f32_e32 v45, 0x3fb8aa3b, v45
	v_exp_f32_e32 v45, v45
	s_nop 0
	v_add_f32_e32 v45, 1.0, v45
	v_rcp_f32_e32 v45, v45
	s_nop 0
	v_mul_f32_e32 v44, v45, v44
	v_mul_f32_e32 v40, v40, v44
	v_and_b32_e32 v44, 0xffff0000, v112
	v_mul_f32_e32 v45, 0x3d372713, v44
	v_mul_f32_e32 v45, v45, v44
	v_fma_f32 v45, v45, v44, v44
	v_mul_f32_e32 v45, 0x3f4c422a, v45
	v_mul_f32_e32 v45, -2.0, v45
	v_mul_f32_e32 v45, 0x3fb8aa3b, v45
	v_exp_f32_e32 v45, v45
	s_nop 0
	v_add_f32_e32 v45, 1.0, v45
	v_rcp_f32_e32 v45, v45
	s_nop 0
	v_mul_f32_e32 v44, v45, v44
	v_mul_f32_e32 v41, v41, v44
	v_cvt_pk_bf16_f32 v40, v40, v41
	v_lshlrev_b32_e32 v41, 16, v113
	v_mul_f32_e32 v44, 0x3d372713, v41
	v_mul_f32_e32 v44, v44, v41
	v_fma_f32 v44, v44, v41, v41
	v_mul_f32_e32 v44, 0x3f4c422a, v44
	v_mul_f32_e32 v44, -2.0, v44
	v_mul_f32_e32 v44, 0x3fb8aa3b, v44
	v_exp_f32_e32 v44, v44
	s_nop 0
	v_add_f32_e32 v44, 1.0, v44
	v_rcp_f32_e32 v44, v44
	s_nop 0
	v_mul_f32_e32 v41, v44, v41
	v_mul_f32_e32 v41, v42, v41
	v_and_b32_e32 v42, 0xffff0000, v113
	v_mul_f32_e32 v44, 0x3d372713, v42
	v_mul_f32_e32 v44, v44, v42
	v_fma_f32 v44, v44, v42, v42
	v_mul_f32_e32 v44, 0x3f4c422a, v44
	v_mul_f32_e32 v44, -2.0, v44
	v_mul_f32_e32 v44, 0x3fb8aa3b, v44
	v_exp_f32_e32 v44, v44
	s_nop 0
	v_add_f32_e32 v44, 1.0, v44
	v_rcp_f32_e32 v44, v44
	s_nop 0
	v_mul_f32_e32 v42, v44, v42
	v_mul_f32_e32 v42, v43, v42
	v_cvt_pk_bf16_f32 v41, v41, v42
	global_store_dwordx2 v[46:47], v[40:41], off offset:1056
	v_lshlrev_b32_e32 v40, 16, v110
	v_mul_f32_e32 v41, 0x3d372713, v40
	v_mul_f32_e32 v41, v41, v40
	v_fma_f32 v41, v41, v40, v40
	v_mul_f32_e32 v41, 0x3f4c422a, v41
	v_mul_f32_e32 v41, -2.0, v41
	v_mul_f32_e32 v41, 0x3fb8aa3b, v41
	v_exp_f32_e32 v41, v41
	s_nop 0
	v_add_f32_e32 v41, 1.0, v41
	v_rcp_f32_e32 v41, v41
	s_nop 0
	v_mul_f32_e32 v40, v41, v40
	v_mul_f32_e32 v36, v36, v40
	v_and_b32_e32 v40, 0xffff0000, v110
	v_mul_f32_e32 v41, 0x3d372713, v40
	v_mul_f32_e32 v41, v41, v40
	v_fma_f32 v41, v41, v40, v40
	v_mul_f32_e32 v41, 0x3f4c422a, v41
	v_mul_f32_e32 v41, -2.0, v41
	v_mul_f32_e32 v41, 0x3fb8aa3b, v41
	v_exp_f32_e32 v41, v41
	s_nop 0
	v_add_f32_e32 v41, 1.0, v41
	v_rcp_f32_e32 v41, v41
	s_nop 0
	v_mul_f32_e32 v40, v41, v40
	v_mul_f32_e32 v37, v37, v40
	v_cvt_pk_bf16_f32 v36, v36, v37
	v_lshlrev_b32_e32 v37, 16, v111
	v_mul_f32_e32 v40, 0x3d372713, v37
	v_mul_f32_e32 v40, v40, v37
	v_fma_f32 v40, v40, v37, v37
	v_mul_f32_e32 v40, 0x3f4c422a, v40
	v_mul_f32_e32 v40, -2.0, v40
	v_mul_f32_e32 v40, 0x3fb8aa3b, v40
	v_exp_f32_e32 v40, v40
	s_nop 0
	v_add_f32_e32 v40, 1.0, v40
	v_rcp_f32_e32 v40, v40
	s_nop 0
	v_mul_f32_e32 v37, v40, v37
	v_mul_f32_e32 v37, v38, v37
	v_and_b32_e32 v38, 0xffff0000, v111
	v_mul_f32_e32 v40, 0x3d372713, v38
	v_mul_f32_e32 v40, v40, v38
	v_fma_f32 v40, v40, v38, v38
	v_mul_f32_e32 v40, 0x3f4c422a, v40
	v_mul_f32_e32 v40, -2.0, v40
	v_mul_f32_e32 v40, 0x3fb8aa3b, v40
	v_exp_f32_e32 v40, v40
	s_nop 0
	v_add_f32_e32 v40, 1.0, v40
	v_rcp_f32_e32 v40, v40
	s_nop 0
	v_mul_f32_e32 v38, v40, v38
	v_mul_f32_e32 v38, v39, v38
	v_cvt_pk_bf16_f32 v37, v37, v38
	global_store_dwordx2 v[46:47], v[36:37], off offset:1088
	v_lshlrev_b32_e32 v36, 16, v108
	v_mul_f32_e32 v37, 0x3d372713, v36
	v_mul_f32_e32 v37, v37, v36
	v_fma_f32 v37, v37, v36, v36
	v_mul_f32_e32 v37, 0x3f4c422a, v37
	v_mul_f32_e32 v37, -2.0, v37
	v_mul_f32_e32 v37, 0x3fb8aa3b, v37
	v_exp_f32_e32 v37, v37
	s_nop 0
	v_add_f32_e32 v37, 1.0, v37
	v_rcp_f32_e32 v37, v37
	s_nop 0
	v_mul_f32_e32 v36, v37, v36
	v_mul_f32_e32 v32, v32, v36
	v_and_b32_e32 v36, 0xffff0000, v108
	v_mul_f32_e32 v37, 0x3d372713, v36
	v_mul_f32_e32 v37, v37, v36
	v_fma_f32 v37, v37, v36, v36
	v_mul_f32_e32 v37, 0x3f4c422a, v37
	v_mul_f32_e32 v37, -2.0, v37
	v_mul_f32_e32 v37, 0x3fb8aa3b, v37
	v_exp_f32_e32 v37, v37
	s_nop 0
	v_add_f32_e32 v37, 1.0, v37
	v_rcp_f32_e32 v37, v37
	s_nop 0
	v_mul_f32_e32 v36, v37, v36
	v_mul_f32_e32 v33, v33, v36
	v_cvt_pk_bf16_f32 v32, v32, v33
	v_lshlrev_b32_e32 v33, 16, v109
	v_mul_f32_e32 v36, 0x3d372713, v33
	v_mul_f32_e32 v36, v36, v33
	v_fma_f32 v36, v36, v33, v33
	v_mul_f32_e32 v36, 0x3f4c422a, v36
	v_mul_f32_e32 v36, -2.0, v36
	v_mul_f32_e32 v36, 0x3fb8aa3b, v36
	v_exp_f32_e32 v36, v36
	s_nop 0
	v_add_f32_e32 v36, 1.0, v36
	v_rcp_f32_e32 v36, v36
	s_nop 0
	v_mul_f32_e32 v33, v36, v33
	v_mul_f32_e32 v33, v34, v33
	v_and_b32_e32 v34, 0xffff0000, v109
	v_mul_f32_e32 v36, 0x3d372713, v34
	v_mul_f32_e32 v36, v36, v34
	v_fma_f32 v36, v36, v34, v34
	v_mul_f32_e32 v36, 0x3f4c422a, v36
	v_mul_f32_e32 v36, -2.0, v36
	v_mul_f32_e32 v36, 0x3fb8aa3b, v36
	v_exp_f32_e32 v36, v36
	s_nop 0
	v_add_f32_e32 v36, 1.0, v36
	v_rcp_f32_e32 v36, v36
	s_nop 0
	v_mul_f32_e32 v34, v36, v34
	v_mul_f32_e32 v34, v35, v34
	v_cvt_pk_bf16_f32 v33, v33, v34
	v_lshlrev_b32_e32 v34, 16, v104
	v_mul_f32_e32 v35, 0x3d372713, v34
	v_mul_f32_e32 v35, v35, v34
	v_fma_f32 v35, v35, v34, v34
	v_mul_f32_e32 v35, 0x3f4c422a, v35
	v_mul_f32_e32 v35, -2.0, v35
	v_mul_f32_e32 v35, 0x3fb8aa3b, v35
	v_exp_f32_e32 v35, v35
	global_store_dwordx2 v[46:47], v[32:33], off offset:1120
	v_lshlrev_b64 v[32:33], 11, v[106:107]
	v_add_f32_e32 v35, 1.0, v35
	v_rcp_f32_e32 v35, v35
	s_nop 0
	v_mul_f32_e32 v34, v35, v34
	v_mul_f32_e32 v28, v28, v34
	v_and_b32_e32 v34, 0xffff0000, v104
	v_mul_f32_e32 v35, 0x3d372713, v34
	v_mul_f32_e32 v35, v35, v34
	v_fma_f32 v35, v35, v34, v34
	v_mul_f32_e32 v35, 0x3f4c422a, v35
	v_mul_f32_e32 v35, -2.0, v35
	v_mul_f32_e32 v35, 0x3fb8aa3b, v35
	v_exp_f32_e32 v35, v35
	s_nop 0
	v_add_f32_e32 v35, 1.0, v35
	v_rcp_f32_e32 v35, v35
	s_nop 0
	v_mul_f32_e32 v34, v35, v34
	v_mul_f32_e32 v29, v29, v34
	v_cvt_pk_bf16_f32 v28, v28, v29
	v_lshlrev_b32_e32 v29, 16, v105
	v_mul_f32_e32 v34, 0x3d372713, v29
	v_mul_f32_e32 v34, v34, v29
	v_fma_f32 v34, v34, v29, v29
	v_mul_f32_e32 v34, 0x3f4c422a, v34
	v_mul_f32_e32 v34, -2.0, v34
	v_mul_f32_e32 v34, 0x3fb8aa3b, v34
	v_exp_f32_e32 v34, v34
	s_nop 0
	v_add_f32_e32 v34, 1.0, v34
	v_rcp_f32_e32 v34, v34
	s_nop 0
	v_mul_f32_e32 v29, v34, v29
	v_mul_f32_e32 v29, v30, v29
	v_and_b32_e32 v30, 0xffff0000, v105
	v_mul_f32_e32 v34, 0x3d372713, v30
	v_mul_f32_e32 v34, v34, v30
	v_fma_f32 v34, v34, v30, v30
	v_mul_f32_e32 v34, 0x3f4c422a, v34
	v_mul_f32_e32 v34, -2.0, v34
	v_mul_f32_e32 v34, 0x3fb8aa3b, v34
	v_exp_f32_e32 v34, v34
	s_nop 0
	v_add_f32_e32 v34, 1.0, v34
	v_rcp_f32_e32 v34, v34
	s_nop 0
	v_mul_f32_e32 v30, v34, v30
	v_mul_f32_e32 v30, v31, v30
	v_cvt_pk_bf16_f32 v29, v29, v30
	v_lshl_add_u64 v[30:31], v[86:87], 0, v[32:33]
	global_store_dwordx2 v[30:31], v[28:29], off offset:1024
	v_lshlrev_b32_e32 v28, 16, v102
	v_mul_f32_e32 v29, 0x3d372713, v28
	v_mul_f32_e32 v29, v29, v28
	v_fma_f32 v29, v29, v28, v28
	v_mul_f32_e32 v29, 0x3f4c422a, v29
	v_mul_f32_e32 v29, -2.0, v29
	v_mul_f32_e32 v29, 0x3fb8aa3b, v29
	v_exp_f32_e32 v29, v29
	s_nop 0
	v_add_f32_e32 v29, 1.0, v29
	v_rcp_f32_e32 v29, v29
	s_nop 0
	v_mul_f32_e32 v28, v29, v28
	v_mul_f32_e32 v24, v24, v28
	v_and_b32_e32 v28, 0xffff0000, v102
	v_mul_f32_e32 v29, 0x3d372713, v28
	v_mul_f32_e32 v29, v29, v28
	v_fma_f32 v29, v29, v28, v28
	v_mul_f32_e32 v29, 0x3f4c422a, v29
	v_mul_f32_e32 v29, -2.0, v29
	v_mul_f32_e32 v29, 0x3fb8aa3b, v29
	v_exp_f32_e32 v29, v29
	s_nop 0
	v_add_f32_e32 v29, 1.0, v29
	v_rcp_f32_e32 v29, v29
	s_nop 0
	v_mul_f32_e32 v28, v29, v28
	v_mul_f32_e32 v25, v25, v28
	v_cvt_pk_bf16_f32 v24, v24, v25
	v_lshlrev_b32_e32 v25, 16, v103
	v_mul_f32_e32 v28, 0x3d372713, v25
	v_mul_f32_e32 v28, v28, v25
	v_fma_f32 v28, v28, v25, v25
	v_mul_f32_e32 v28, 0x3f4c422a, v28
	v_mul_f32_e32 v28, -2.0, v28
	v_mul_f32_e32 v28, 0x3fb8aa3b, v28
	v_exp_f32_e32 v28, v28
	s_nop 0
	v_add_f32_e32 v28, 1.0, v28
	v_rcp_f32_e32 v28, v28
	s_nop 0
	v_mul_f32_e32 v25, v28, v25
	v_mul_f32_e32 v25, v26, v25
	v_and_b32_e32 v26, 0xffff0000, v103
	v_mul_f32_e32 v28, 0x3d372713, v26
	v_mul_f32_e32 v28, v28, v26
	v_fma_f32 v28, v28, v26, v26
	v_mul_f32_e32 v28, 0x3f4c422a, v28
	v_mul_f32_e32 v28, -2.0, v28
	v_mul_f32_e32 v28, 0x3fb8aa3b, v28
	v_exp_f32_e32 v28, v28
	s_nop 0
	v_add_f32_e32 v28, 1.0, v28
	v_rcp_f32_e32 v28, v28
	s_nop 0
	v_mul_f32_e32 v26, v28, v26
	v_mul_f32_e32 v26, v27, v26
	v_cvt_pk_bf16_f32 v25, v25, v26
	global_store_dwordx2 v[30:31], v[24:25], off offset:1056
	v_lshlrev_b32_e32 v24, 16, v100
	v_mul_f32_e32 v25, 0x3d372713, v24
	v_mul_f32_e32 v25, v25, v24
	v_fma_f32 v25, v25, v24, v24
	v_mul_f32_e32 v25, 0x3f4c422a, v25
	v_mul_f32_e32 v25, -2.0, v25
	v_mul_f32_e32 v25, 0x3fb8aa3b, v25
	v_exp_f32_e32 v25, v25
	s_nop 0
	v_add_f32_e32 v25, 1.0, v25
	v_rcp_f32_e32 v25, v25
	s_nop 0
	v_mul_f32_e32 v24, v25, v24
	v_mul_f32_e32 v20, v20, v24
	v_and_b32_e32 v24, 0xffff0000, v100
	v_mul_f32_e32 v25, 0x3d372713, v24
	v_mul_f32_e32 v25, v25, v24
	v_fma_f32 v25, v25, v24, v24
	v_mul_f32_e32 v25, 0x3f4c422a, v25
	v_mul_f32_e32 v25, -2.0, v25
	v_mul_f32_e32 v25, 0x3fb8aa3b, v25
	v_exp_f32_e32 v25, v25
	s_nop 0
	v_add_f32_e32 v25, 1.0, v25
	v_rcp_f32_e32 v25, v25
	s_nop 0
	v_mul_f32_e32 v24, v25, v24
	v_mul_f32_e32 v21, v21, v24
	v_cvt_pk_bf16_f32 v20, v20, v21
	v_lshlrev_b32_e32 v21, 16, v101
	v_mul_f32_e32 v24, 0x3d372713, v21
	v_mul_f32_e32 v24, v24, v21
	v_fma_f32 v24, v24, v21, v21
	v_mul_f32_e32 v24, 0x3f4c422a, v24
	v_mul_f32_e32 v24, -2.0, v24
	v_mul_f32_e32 v24, 0x3fb8aa3b, v24
	v_exp_f32_e32 v24, v24
	s_nop 0
	v_add_f32_e32 v24, 1.0, v24
	v_rcp_f32_e32 v24, v24
	s_nop 0
	v_mul_f32_e32 v21, v24, v21
	v_mul_f32_e32 v21, v22, v21
	v_and_b32_e32 v22, 0xffff0000, v101
	v_mul_f32_e32 v24, 0x3d372713, v22
	v_mul_f32_e32 v24, v24, v22
	v_fma_f32 v24, v24, v22, v22
	v_mul_f32_e32 v24, 0x3f4c422a, v24
	v_mul_f32_e32 v24, -2.0, v24
	v_mul_f32_e32 v24, 0x3fb8aa3b, v24
	v_exp_f32_e32 v24, v24
	s_nop 0
	v_add_f32_e32 v24, 1.0, v24
	v_rcp_f32_e32 v24, v24
	s_nop 0
	v_mul_f32_e32 v22, v24, v22
	v_mul_f32_e32 v22, v23, v22
	v_cvt_pk_bf16_f32 v21, v21, v22
	global_store_dwordx2 v[30:31], v[20:21], off offset:1088
	v_lshlrev_b32_e32 v20, 16, v98
	v_mul_f32_e32 v21, 0x3d372713, v20
	v_mul_f32_e32 v21, v21, v20
	v_fma_f32 v21, v21, v20, v20
	v_mul_f32_e32 v21, 0x3f4c422a, v21
	v_mul_f32_e32 v21, -2.0, v21
	v_mul_f32_e32 v21, 0x3fb8aa3b, v21
	v_exp_f32_e32 v21, v21
	s_nop 0
	v_add_f32_e32 v21, 1.0, v21
	v_rcp_f32_e32 v21, v21
	s_nop 0
	v_mul_f32_e32 v20, v21, v20
	v_mul_f32_e32 v16, v16, v20
	v_and_b32_e32 v20, 0xffff0000, v98
	v_mul_f32_e32 v21, 0x3d372713, v20
	v_mul_f32_e32 v21, v21, v20
	v_fma_f32 v21, v21, v20, v20
	v_mul_f32_e32 v21, 0x3f4c422a, v21
	v_mul_f32_e32 v21, -2.0, v21
	v_mul_f32_e32 v21, 0x3fb8aa3b, v21
	v_exp_f32_e32 v21, v21
	s_nop 0
	v_add_f32_e32 v21, 1.0, v21
	v_rcp_f32_e32 v21, v21
	s_nop 0
	v_mul_f32_e32 v20, v21, v20
	v_mul_f32_e32 v17, v17, v20
	v_cvt_pk_bf16_f32 v16, v16, v17
	v_lshlrev_b32_e32 v17, 16, v99
	v_mul_f32_e32 v20, 0x3d372713, v17
	v_mul_f32_e32 v20, v20, v17
	v_fma_f32 v20, v20, v17, v17
	v_mul_f32_e32 v20, 0x3f4c422a, v20
	v_mul_f32_e32 v20, -2.0, v20
	v_mul_f32_e32 v20, 0x3fb8aa3b, v20
	v_exp_f32_e32 v20, v20
	s_nop 0
	v_add_f32_e32 v20, 1.0, v20
	v_rcp_f32_e32 v20, v20
	s_nop 0
	v_mul_f32_e32 v17, v20, v17
	v_mul_f32_e32 v17, v18, v17
	v_and_b32_e32 v18, 0xffff0000, v99
	v_mul_f32_e32 v20, 0x3d372713, v18
	v_mul_f32_e32 v20, v20, v18
	v_fma_f32 v20, v20, v18, v18
	v_mul_f32_e32 v20, 0x3f4c422a, v20
	v_mul_f32_e32 v20, -2.0, v20
	v_mul_f32_e32 v20, 0x3fb8aa3b, v20
	v_exp_f32_e32 v20, v20
	s_nop 0
	v_add_f32_e32 v20, 1.0, v20
	v_rcp_f32_e32 v20, v20
	s_nop 0
	v_mul_f32_e32 v18, v20, v18
	v_mul_f32_e32 v18, v19, v18
	v_cvt_pk_bf16_f32 v17, v17, v18
	s_waitcnt vmcnt(14)
	v_lshlrev_b32_e32 v18, 16, v94
	v_mul_f32_e32 v19, 0x3d372713, v18
	v_mul_f32_e32 v19, v19, v18
	v_fma_f32 v19, v19, v18, v18
	v_mul_f32_e32 v19, 0x3f4c422a, v19
	v_mul_f32_e32 v19, -2.0, v19
	v_mul_f32_e32 v19, 0x3fb8aa3b, v19
	v_exp_f32_e32 v19, v19
	global_store_dwordx2 v[30:31], v[16:17], off offset:1120
	v_lshlrev_b64 v[16:17], 11, v[96:97]
	v_add_f32_e32 v19, 1.0, v19
	v_rcp_f32_e32 v19, v19
	s_nop 0
	v_mul_f32_e32 v18, v19, v18
	v_mul_f32_e32 v12, v12, v18
	v_and_b32_e32 v18, 0xffff0000, v94
	v_mul_f32_e32 v19, 0x3d372713, v18
	v_mul_f32_e32 v19, v19, v18
	v_fma_f32 v19, v19, v18, v18
	v_mul_f32_e32 v19, 0x3f4c422a, v19
	v_mul_f32_e32 v19, -2.0, v19
	v_mul_f32_e32 v19, 0x3fb8aa3b, v19
	v_exp_f32_e32 v19, v19
	s_nop 0
	v_add_f32_e32 v19, 1.0, v19
	v_rcp_f32_e32 v19, v19
	s_nop 0
	v_mul_f32_e32 v18, v19, v18
	v_mul_f32_e32 v13, v13, v18
	v_cvt_pk_bf16_f32 v12, v12, v13
	v_lshlrev_b32_e32 v13, 16, v95
	v_mul_f32_e32 v18, 0x3d372713, v13
	v_mul_f32_e32 v18, v18, v13
	v_fma_f32 v18, v18, v13, v13
	v_mul_f32_e32 v18, 0x3f4c422a, v18
	v_mul_f32_e32 v18, -2.0, v18
	v_mul_f32_e32 v18, 0x3fb8aa3b, v18
	v_exp_f32_e32 v18, v18
	s_nop 0
	v_add_f32_e32 v18, 1.0, v18
	v_rcp_f32_e32 v18, v18
	s_nop 0
	v_mul_f32_e32 v13, v18, v13
	v_mul_f32_e32 v13, v14, v13
	v_and_b32_e32 v14, 0xffff0000, v95
	v_mul_f32_e32 v18, 0x3d372713, v14
	v_mul_f32_e32 v18, v18, v14
	v_fma_f32 v18, v18, v14, v14
	v_mul_f32_e32 v18, 0x3f4c422a, v18
	v_mul_f32_e32 v18, -2.0, v18
	v_mul_f32_e32 v18, 0x3fb8aa3b, v18
	v_exp_f32_e32 v18, v18
	s_nop 0
	v_add_f32_e32 v18, 1.0, v18
	v_rcp_f32_e32 v18, v18
	s_nop 0
	v_mul_f32_e32 v14, v18, v14
	v_mul_f32_e32 v14, v15, v14
	v_cvt_pk_bf16_f32 v13, v13, v14
	v_lshl_add_u64 v[14:15], v[86:87], 0, v[16:17]
	global_store_dwordx2 v[14:15], v[12:13], off offset:1024
	s_waitcnt vmcnt(15)
	v_lshlrev_b32_e32 v12, 16, v92
	v_mul_f32_e32 v13, 0x3d372713, v12
	v_mul_f32_e32 v13, v13, v12
	v_fma_f32 v13, v13, v12, v12
	v_mul_f32_e32 v13, 0x3f4c422a, v13
	v_mul_f32_e32 v13, -2.0, v13
	v_mul_f32_e32 v13, 0x3fb8aa3b, v13
	v_exp_f32_e32 v13, v13
	s_nop 0
	v_add_f32_e32 v13, 1.0, v13
	v_rcp_f32_e32 v13, v13
	s_nop 0
	v_mul_f32_e32 v12, v13, v12
	v_mul_f32_e32 v8, v8, v12
	v_and_b32_e32 v12, 0xffff0000, v92
	v_mul_f32_e32 v13, 0x3d372713, v12
	v_mul_f32_e32 v13, v13, v12
	v_fma_f32 v13, v13, v12, v12
	v_mul_f32_e32 v13, 0x3f4c422a, v13
	v_mul_f32_e32 v13, -2.0, v13
	v_mul_f32_e32 v13, 0x3fb8aa3b, v13
	v_exp_f32_e32 v13, v13
	s_nop 0
	v_add_f32_e32 v13, 1.0, v13
	v_rcp_f32_e32 v13, v13
	s_nop 0
	v_mul_f32_e32 v12, v13, v12
	v_mul_f32_e32 v9, v9, v12
	v_cvt_pk_bf16_f32 v8, v8, v9
	v_lshlrev_b32_e32 v9, 16, v93
	v_mul_f32_e32 v12, 0x3d372713, v9
	v_mul_f32_e32 v12, v12, v9
	v_fma_f32 v12, v12, v9, v9
	v_mul_f32_e32 v12, 0x3f4c422a, v12
	v_mul_f32_e32 v12, -2.0, v12
	v_mul_f32_e32 v12, 0x3fb8aa3b, v12
	v_exp_f32_e32 v12, v12
	s_nop 0
	v_add_f32_e32 v12, 1.0, v12
	v_rcp_f32_e32 v12, v12
	s_nop 0
	v_mul_f32_e32 v9, v12, v9
	v_mul_f32_e32 v9, v10, v9
	v_and_b32_e32 v10, 0xffff0000, v93
	v_mul_f32_e32 v12, 0x3d372713, v10
	v_mul_f32_e32 v12, v12, v10
	v_fma_f32 v12, v12, v10, v10
	v_mul_f32_e32 v12, 0x3f4c422a, v12
	v_mul_f32_e32 v12, -2.0, v12
	v_mul_f32_e32 v12, 0x3fb8aa3b, v12
	v_exp_f32_e32 v12, v12
	s_nop 0
	v_add_f32_e32 v12, 1.0, v12
	v_rcp_f32_e32 v12, v12
	s_nop 0
	v_mul_f32_e32 v10, v12, v10
	v_mul_f32_e32 v10, v11, v10
	v_cvt_pk_bf16_f32 v9, v9, v10
	global_store_dwordx2 v[14:15], v[8:9], off offset:1056
	s_waitcnt vmcnt(15)
	v_lshlrev_b32_e32 v8, 16, v90
	v_mul_f32_e32 v9, 0x3d372713, v8
	v_mul_f32_e32 v9, v9, v8
	v_fma_f32 v9, v9, v8, v8
	v_mul_f32_e32 v9, 0x3f4c422a, v9
	v_mul_f32_e32 v9, -2.0, v9
	v_mul_f32_e32 v9, 0x3fb8aa3b, v9
	v_exp_f32_e32 v9, v9
	s_nop 0
	v_add_f32_e32 v9, 1.0, v9
	v_rcp_f32_e32 v9, v9
	s_nop 0
	v_mul_f32_e32 v8, v9, v8
	v_mul_f32_e32 v4, v4, v8
	v_and_b32_e32 v8, 0xffff0000, v90
	v_mul_f32_e32 v9, 0x3d372713, v8
	v_mul_f32_e32 v9, v9, v8
	v_fma_f32 v9, v9, v8, v8
	v_mul_f32_e32 v9, 0x3f4c422a, v9
	v_mul_f32_e32 v9, -2.0, v9
	v_mul_f32_e32 v9, 0x3fb8aa3b, v9
	v_exp_f32_e32 v9, v9
	s_nop 0
	v_add_f32_e32 v9, 1.0, v9
	v_rcp_f32_e32 v9, v9
	s_nop 0
	v_mul_f32_e32 v8, v9, v8
	v_mul_f32_e32 v5, v5, v8
	v_cvt_pk_bf16_f32 v4, v4, v5
	v_lshlrev_b32_e32 v5, 16, v91
	v_mul_f32_e32 v8, 0x3d372713, v5
	v_mul_f32_e32 v8, v8, v5
	v_fma_f32 v8, v8, v5, v5
	v_mul_f32_e32 v8, 0x3f4c422a, v8
	v_mul_f32_e32 v8, -2.0, v8
	v_mul_f32_e32 v8, 0x3fb8aa3b, v8
	v_exp_f32_e32 v8, v8
	s_nop 0
	v_add_f32_e32 v8, 1.0, v8
	v_rcp_f32_e32 v8, v8
	s_nop 0
	v_mul_f32_e32 v5, v8, v5
	v_mul_f32_e32 v5, v6, v5
	v_and_b32_e32 v6, 0xffff0000, v91
	v_mul_f32_e32 v8, 0x3d372713, v6
	v_mul_f32_e32 v8, v8, v6
	v_fma_f32 v8, v8, v6, v6
	v_mul_f32_e32 v8, 0x3f4c422a, v8
	v_mul_f32_e32 v8, -2.0, v8
	v_mul_f32_e32 v8, 0x3fb8aa3b, v8
	v_exp_f32_e32 v8, v8
	s_nop 0
	v_add_f32_e32 v8, 1.0, v8
	v_rcp_f32_e32 v8, v8
	s_nop 0
	v_mul_f32_e32 v6, v8, v6
	v_mul_f32_e32 v6, v7, v6
	v_cvt_pk_bf16_f32 v5, v5, v6
	global_store_dwordx2 v[14:15], v[4:5], off offset:1088
	s_waitcnt vmcnt(15)
	v_lshlrev_b32_e32 v4, 16, v88
	v_mul_f32_e32 v5, 0x3d372713, v4
	v_mul_f32_e32 v5, v5, v4
	v_fma_f32 v5, v5, v4, v4
	v_mul_f32_e32 v5, 0x3f4c422a, v5
	v_mul_f32_e32 v5, -2.0, v5
	v_mul_f32_e32 v5, 0x3fb8aa3b, v5
	v_exp_f32_e32 v5, v5
	s_nop 0
	v_add_f32_e32 v5, 1.0, v5
	v_rcp_f32_e32 v5, v5
	s_nop 0
	v_mul_f32_e32 v4, v5, v4
	v_mul_f32_e32 v0, v0, v4
	v_and_b32_e32 v4, 0xffff0000, v88
	v_mul_f32_e32 v5, 0x3d372713, v4
	v_mul_f32_e32 v5, v5, v4
	v_fma_f32 v5, v5, v4, v4
	v_mul_f32_e32 v5, 0x3f4c422a, v5
	v_mul_f32_e32 v5, -2.0, v5
	v_mul_f32_e32 v5, 0x3fb8aa3b, v5
	v_exp_f32_e32 v5, v5
	s_nop 0
	v_add_f32_e32 v5, 1.0, v5
	v_rcp_f32_e32 v5, v5
	s_nop 0
	v_mul_f32_e32 v4, v5, v4
	v_mul_f32_e32 v1, v1, v4
	v_cvt_pk_bf16_f32 v0, v0, v1
	v_lshlrev_b32_e32 v1, 16, v89
	v_mul_f32_e32 v4, 0x3d372713, v1
	v_mul_f32_e32 v4, v4, v1
	v_fma_f32 v4, v4, v1, v1
	v_mul_f32_e32 v4, 0x3f4c422a, v4
	v_mul_f32_e32 v4, -2.0, v4
	v_mul_f32_e32 v4, 0x3fb8aa3b, v4
	v_exp_f32_e32 v4, v4
	s_nop 0
	v_add_f32_e32 v4, 1.0, v4
	v_rcp_f32_e32 v4, v4
	s_nop 0
	v_mul_f32_e32 v1, v4, v1
	v_mul_f32_e32 v1, v2, v1
	v_and_b32_e32 v2, 0xffff0000, v89
	v_mul_f32_e32 v4, 0x3d372713, v2
	v_mul_f32_e32 v4, v4, v2
	v_fma_f32 v4, v4, v2, v2
	v_mul_f32_e32 v4, 0x3f4c422a, v4
	v_mul_f32_e32 v4, -2.0, v4
	v_mul_f32_e32 v4, 0x3fb8aa3b, v4
	v_exp_f32_e32 v4, v4
	s_nop 0
	v_add_f32_e32 v4, 1.0, v4
	v_rcp_f32_e32 v4, v4
	s_nop 0
	v_mul_f32_e32 v2, v4, v2
	v_mul_f32_e32 v2, v3, v2
	v_cvt_pk_bf16_f32 v1, v1, v2
	global_store_dwordx2 v[14:15], v[0:1], off offset:1120
	s_cbranch_scc1 .LBB0_310
